# v9 stack + P7 K-loop restructured to one workgroup rendezvous per super-phase (leading half LS,MM,barrier; trailing half LS,barrier,MM; no stagger/restore barrier, unconditional join; mid-run s_setpri
# speedup vs baseline: 1.0041x; 1.0028x over previous
; #define PG8_STAGE(bufoff, gbase, voff) do { _Pragma("unroll") for (int _i = 0; _i < 2; ++_i) \
;         __builtin_amdgcn_global_load_lds((const unsigned*)((const char*)(gbase) + (voff)[_i]), (PG8_LAS unsigned*)(lds + (bufoff) + ldsw + _i * 8192), 16, 0, 0); } while (0)
; #define PG8_WAIT_V(n) asm volatile("s_waitcnt vmcnt(" #n ")" ::: "memory")
; #define PG8_BAR __builtin_amdgcn_s_barrier()
; template <class Epi, class Sched, bool ALIGN_EPI = false, bool SP2 = false>
; __device__ __forceinline__ void gemm_phase(PG8_LAS unsigned char* lds, const Gemm g, const Sched& S, const Epi& E) {
;     ...
;     const int tid = tid_, wid = __builtin_amdgcn_readfirstlane(tid >> 6), lane = tid & 63, wr = wid >> 2, wc = wid & 3, fr = lane & 15, fq = lane >> 4;
;     const int K = g.K, nt = K / BK;
;     unsigned voffA[2], voffB[2];
; #pragma unroll
;     for (int i = 0; i < 2; ++i) { int R, C; stage_rc(tid * 16 + i * 8192, R, C); const int Rb = Epi::PERM ? ((R & ~31) + perm32(R & 31)) : R;
;         voffA[i] = (unsigned)(R * K + C) * 2u; voffB[i] = (unsigned)(Rb * K + C) * 2u; }
;     const size_t kstep = (size_t)(BK * 2);
;     const size_t hstep = (size_t)HALF * K * 2;
;     const size_t tstep = 2 * hstep;
;     const unsigned ldsw = (unsigned)wid * 1024u;
;     const int aoff = lds_byte(wr * 64 + fr, fq * 8), boff = lds_byte(wc * 32 + fr, fq * 8);
;     ...
;     const char* cA = (const char*)g.A + (size_t)cur.pm * tstep; const char* cB = (const char*)g.Bt + (size_t)cur.pn * tstep;
;     S.a_ready(cur);
;     if constexpr (SP2) {
;         PG8_STAGE(PG8_SB(0, 0), cB, voffB); PG8_STAGE(PG8_SB(0, 1), cB + hstep, voffB); PG8_STAGE(PG8_SA(0, 0), cA, voffA); PG8_STAGE(PG8_SA(0, 1), cA + hstep, voffA);
;         if (wr == 1) PG8_BAR;
;         PG8_WAIT_V(2); PG8_BAR;
;         PG8_STAGE(PG8_SB(1, 0), cB + kstep, voffB); PG8_STAGE(PG8_SA(1, 0), cA + kstep, voffA); PG8_STAGE(PG8_SB(1, 1), cB + hstep + kstep, voffB);
;         PG8_WAIT_V(6); PG8_BAR;
.LBB0_980:
	v_ashrrev_i32_e32 v2, 31, v10
	v_lshrrev_b32_e32 v2, 26, v2
	v_add_u32_e32 v2, v10, v2
	v_ashrrev_i32_e32 v11, 6, v2
	v_bfe_i32 v2, v10, 27, 1
	v_lshlrev_b32_e32 v1, 4, v10
	v_lshrrev_b32_e32 v2, 22, v2
	v_add_u32_e32 v2, v1, v2
	v_and_b32_e32 v2, 0xfffffc00, v2
	v_sub_u32_e32 v2, v1, v2
	v_lshrrev_b32_e32 v3, 4, v2
	v_bitop3_b32 v2, v3, v2, 32 bitop3:0x6c
	v_ashrrev_i32_e32 v4, 31, v2
	v_lshrrev_b32_e32 v4, 26, v4
	v_add_u32_e32 v4, v2, v4
	v_lshlrev_b32_e32 v3, 3, v11
	v_ashrrev_i32_e32 v12, 6, v4
	v_and_b32_e32 v4, 0xc0, v4
	v_and_b32_e32 v3, -16, v3
	v_sub_u32_e32 v2, v2, v4
	v_mov_b32_e32 v4, 1
	v_add_u32_e32 v3, v12, v3
	v_ashrrev_i16_sdwa v2, v4, sext(v2) dst_sel:DWORD dst_unused:UNUSED_PAD src0_sel:DWORD src1_sel:BYTE_0
	s_ashr_i32 s0, s7, 3
	v_lshlrev_b32_e32 v5, 5, v11
	v_bfe_i32 v13, v2, 0, 16
	v_lshlrev_b32_e32 v2, 1, v3
	v_lshrrev_b32_e32 v6, 2, v3
	v_and_b32_e32 v7, 3, v12
	s_mov_b32 s7, 0x7ffe0
	v_and_b32_e32 v5, 32, v5
	v_and_b32_e32 v2, 24, v2
	v_and_b32_e32 v6, 4, v6
	v_and_or_b32 v7, v3, s7, v7
	v_or3_b32 v2, v7, v6, v2
	v_add_lshl_u32 v5, v5, v13, 1
	v_add_u32_e32 v1, 0x2000, v1
	v_lshl_add_u32 v132, v2, 13, v5
	v_ashrrev_i32_e32 v2, 31, v1
	v_lshrrev_b32_e32 v2, 22, v2
	v_add_u32_e32 v2, v1, v2
	v_ashrrev_i32_e32 v14, 10, v2
	v_mul_i32_i24_e32 v2, 0x400, v14
	v_sub_u32_e32 v1, v1, v2
	v_lshrrev_b32_e32 v2, 4, v1
	v_bitop3_b32 v1, v2, v1, 32 bitop3:0x6c
	v_lshl_add_u32 v130, v3, 13, v5
	v_ashrrev_i32_e32 v3, 31, v1
	v_lshrrev_b32_e32 v3, 26, v3
	v_add_u32_e32 v3, v1, v3
	s_add_i32 s0, s6, s0
	v_lshlrev_b32_e32 v2, 3, v14
	v_ashrrev_i32_e32 v15, 6, v3
	v_and_b32_e32 v3, 0xc0, v3
	s_ashr_i32 s6, s0, 31
	v_and_b32_e32 v2, -16, v2
	v_sub_u32_e32 v1, v1, v3
	s_lshr_b32 s6, s6, 23
	v_add_u32_e32 v2, v15, v2
	v_ashrrev_i16_sdwa v1, v4, sext(v1) dst_sel:DWORD dst_unused:UNUSED_PAD src0_sel:DWORD src1_sel:BYTE_0
	v_and_b32_e32 v4, 3, v15
	s_add_i32 s6, s0, s6
	v_and_or_b32 v4, v2, s7, v4
	s_ashr_i32 s7, s6, 9
	s_and_b32 s6, s6, 0xfffffe00
	s_sub_i32 s6, s0, s6
	s_sext_i32_i16 s0, s6
	s_bfe_u32 s0, s0, 0x3001c
	s_add_i32 s13, s6, s0
	s_sext_i32_i16 s0, s13
	s_and_b32 s13, s13, 0xfff8
	s_sub_i32 s6, s6, s13
	s_lshl_b32 s7, s7, 3
	s_sext_i32_i16 s6, s6
	s_ashr_i32 s1, s14, 8
	s_lshr_b32 s0, s0, 3
	s_add_i32 s38, s7, s6
	s_ashr_i32 s12, s14, 6
	s_ashr_i32 s39, s38, 31
	s_bfe_i64 s[20:21], s[0:1], 0x100000
	s_lshl_b32 s33, s12, 10
	s_lshl_b64 s[6:7], s[38:39], 21
	s_lshl_b64 s[20:21], s[20:21], 21
	s_add_u32 s42, s76, s20
	v_lshlrev_b32_e32 v5, 5, v14
	v_bfe_i32 v16, v1, 0, 16
	v_lshlrev_b32_e32 v1, 1, v2
	v_lshrrev_b32_e32 v3, 2, v2
	s_addc_u32 s43, s77, s21
	s_add_i32 s39, s33, 0
	v_and_b32_e32 v5, 32, v5
	v_and_b32_e32 v1, 24, v1
	v_and_b32_e32 v3, 4, v3
	s_add_i32 m0, s39, 0x10000
	v_or3_b32 v1, v4, v3, v1
	v_add_lshl_u32 v3, v5, v16, 1
	global_load_lds_dwordx4 v132, s[42:43]
	s_add_i32 m0, s39, 0x12000
	v_lshl_add_u32 v136, v1, 13, v3
	s_add_u32 s20, s42, 0x100000
	global_load_lds_dwordx4 v136, s[42:43]
	s_addc_u32 s21, s43, 0
	s_add_i32 m0, s39, 0x14000
	v_lshl_add_u32 v134, v2, 13, v3
	global_load_lds_dwordx4 v132, s[20:21]
	s_add_i32 m0, s39, 0x16000
	s_add_u32 s40, s74, s6
	v_readlane_b32 s6, v247, 29
	s_addc_u32 s41, s6, s7
	s_add_i32 s46, s39, 0x2000
	global_load_lds_dwordx4 v136, s[20:21]
	s_mov_b32 m0, s39
	s_add_u32 s6, s40, 0x100000
	global_load_lds_dwordx4 v130, s[40:41]
	s_mov_b32 m0, s46
	s_addc_u32 s7, s41, 0
	s_add_i32 s47, s39, 0x4000
	global_load_lds_dwordx4 v134, s[40:41]
	s_mov_b32 m0, s47
	s_add_i32 s48, s39, 0x6000
	global_load_lds_dwordx4 v130, s[6:7]
	s_mov_b32 m0, s48
	v_mov_b32_e32 v133, 0
	global_load_lds_dwordx4 v134, s[6:7]
	v_mov_b32_e32 v137, v133
	v_mov_b32_e32 v131, v133
	v_mov_b32_e32 v135, v133
	s_cmp_eq_u32 s1, 1
	s_mov_b32 s49, 0
	v_lshl_add_u64 v[8:9], s[42:43], 0, v[132:133]
	v_lshl_add_u64 v[6:7], s[42:43], 0, v[136:137]
	v_lshl_add_u64 v[2:3], s[40:41], 0, v[130:131]
	s_cselect_b64 s[6:7], -1, 0
	s_cmp_lg_u32 s1, 1
	v_lshl_add_u64 v[4:5], s[40:41], 0, v[134:135]
	s_cbranch_scc1 .LBB0_982
.LBB0_982:
	s_lshl_b32 s12, s12, 5
	s_and_b32 s22, s12, 0x60
	s_mov_b64 s[12:13], 0x80
	s_add_i32 m0, s39, 0x18000
	v_lshl_add_u64 v[8:9], v[8:9], 0, s[12:13]
	s_lshl_b32 s15, s1, 13
	s_lshl_b32 s23, s22, 7
	s_waitcnt vmcnt(2)
	s_barrier
	global_load_lds_dwordx4 v[8:9], off
	v_lshl_add_u64 v[6:7], v[6:7], 0, s[12:13]
	s_add_i32 m0, s39, 0x1a000
	s_add_i32 s50, s39, 0x8000
	s_add_i32 s51, s39, 0xa000
	global_load_lds_dwordx4 v[6:7], off
	v_lshl_add_u64 v[2:3], v[2:3], 0, s[12:13]
	s_mov_b32 m0, s50
	s_add_u32 s20, s42, 0x100080
	global_load_lds_dwordx4 v[2:3], off
	v_lshl_add_u64 v[2:3], v[4:5], 0, s[12:13]
	s_mov_b32 m0, s51
	s_addc_u32 s21, s43, 0
	global_load_lds_dwordx4 v[2:3], off
	s_add_i32 m0, s39, 0x1c000
	v_lshl_add_u64 v[2:3], s[20:21], 0, v[132:133]
	global_load_lds_dwordx4 v[2:3], off
	v_lshl_add_u64 v[2:3], s[20:21], 0, v[136:137]
	s_add_i32 m0, s39, 0x1e000
	s_cmpk_lt_u32 s14, 0x100
	global_load_lds_dwordx4 v[2:3], off
	v_lshrrev_b32_e32 v3, 1, v10
	v_and_b32_e32 v3, 24, v3
	v_and_b32_e32 v2, 15, v10
	v_lshlrev_b32_e32 v4, 1, v3
	v_lshl_or_b32 v1, s1, 6, v2
	v_lshl_or_b32 v2, v2, 6, v4
	v_lshlrev_b32_e32 v4, 2, v10
	v_and_b32_e32 v4, 32, v4
	v_bitop3_b32 v5, v2, s15, v4 bitop3:0xde
	v_bitop3_b32 v148, v2, s23, v4 bitop3:0xde
	v_lshlrev_b32_e32 v2, 16, v11
	v_and_b32_e32 v2, 0xfffe0000, v2
	v_or_b32_e32 v149, s22, v3
	v_lshl_add_u32 v2, v12, 13, v2
	v_and_b32_e32 v3, 1, v11
	v_lshl_or_b32 v2, v3, 6, v2
	v_lshl_add_u32 v138, v13, 1, v2
	v_lshlrev_b32_e32 v2, 16, v14
	v_and_b32_e32 v2, 0xfffe0000, v2
	s_waitcnt vmcnt(6)
	v_lshl_add_u32 v2, v15, 13, v2
	v_and_b32_e32 v3, 1, v14
	s_cselect_b64 s[14:15], -1, 0
	v_lshl_or_b32 v2, v3, 6, v2
	s_add_i32 s52, 0, 0x10000
	s_add_i32 s53, 0, 0x14000
	s_sext_i32_i16 s58, s0
	v_mov_b32_e32 v139, v133
	v_lshl_add_u32 v140, v16, 1, v2
	v_mov_b32_e32 v141, v133
	v_mov_b64_e32 v[142:143], 0x1000
	v_mov_b64_e32 v[144:145], 0xfff
	v_add_u32_e32 v150, s52, v148
	v_add_u32_e32 v151, s53, v148
	v_add_u32_e32 v152, 0, v5
	s_mov_b64 s[20:21], 0x400000
	s_mov_b32 s54, 0x400000
	s_mov_b64 s[22:23], 0x480000
	s_mov_b32 s55, 0x480000
	s_mov_b64 s[24:25], 0x500000
	s_mov_b32 s56, 0x500000
	s_mov_b64 s[26:27], 0x580000
	s_mov_b32 s57, 0x580000
	s_barrier
	s_branch .LBB0_985

; #define PG8_STAGE(bufoff, gbase, voff) do { _Pragma("unroll") for (int _i = 0; _i < 2; ++_i) \
;         __builtin_amdgcn_global_load_lds((const unsigned*)((const char*)(gbase) + (voff)[_i]), (PG8_LAS unsigned*)(lds + (bufoff) + ldsw + _i * 8192), 16, 0, 0); } while (0)
; #define PG8_LDA(dst, b, h) do { _Pragma("unroll") for (int m = 0; m < 4; ++m) _Pragma("unroll") for (int k = 0; k < 2; ++k) dst[m][k] = *(const PG8_LAS bf16x8*)(lds + PG8_SA(b, h) + aoff + m * 2048 + k * 1024); } while (0)
; #define PG8_LDB(dst, b, h) do { _Pragma("unroll") for (int n = 0; n < 2; ++n) _Pragma("unroll") for (int k = 0; k < 2; ++k) dst[n][k] = *(const PG8_LAS bf16x8*)(lds + PG8_SB(b, h) + boff + n * 2048 + k * 1024); } while (0)
; #define PG8_WAIT_V(n) asm volatile("s_waitcnt vmcnt(" #n ")" ::: "memory")
; #define PG8_WAIT_L(n) asm volatile("s_waitcnt lgkmcnt(" #n ")" ::: "memory")
; #define PG8_BAR __builtin_amdgcn_s_barrier()
; #define PG8_SCHED __builtin_amdgcn_sched_barrier(0)
; template <class Epi, class Sched, bool ALIGN_EPI = false, bool SP2 = false>
; __device__ __forceinline__ void gemm_phase(PG8_LAS unsigned char* lds, const Gemm g, const Sched& S, const Epi& E) {
;     ...
;         const bool has_next = S.next(ui + 1, nxt);
;         const char* nA = has_next ? (const char*)g.A + (size_t)nxt.pm * tstep : cA; const char* nB = has_next ? (const char*)g.Bt + (size_t)nxt.pn * tstep : cB;
;         for (int t = 0; t < nt; t += 2) {
;             const bool last = (t == nt - 2);
;             const char* a1 = cA + (size_t)(t + 1) * kstep;
;             const char* a2 = last ? nA : cA + (size_t)(t + 2) * kstep; const char* b2 = last ? nB : cB + (size_t)(t + 2) * kstep;
;             const char* a3 = a2 + kstep; const char* b3 = b2 + kstep;
;             if (last && has_next) S.a_ready(nxt);
;             if constexpr (SP2) {
;             PG8_LDB(B0, 0, 0); PG8_LDB(B1, 0, 1); PG8_SCHED; PG8_LDA(At, 0, 0); PG8_STAGE(PG8_SA(1, 1), a1 + hstep, voffA);
;             PG8_WAIT_V(8); PG8_WAIT_L(0); PG8_BAR; PG8_MMA(0, 0, At, B0); PG8_MMA(0, 1, At, B1); PG8_BAR; PG8_SCHED;
;     ...
; #pragma unroll
;         for (int a = 0; a < 2; ++a)
; #pragma unroll
;             for (int b = 0; b < 2; ++b)
; #pragma unroll
;                 for (int m = 0; m < 4; ++m)
; #pragma unroll
;                     for (int n = 0; n < 2; ++n) acc[a][b][m][n] = (f32x4){0.f, 0.f, 0.f, 0.f};
.LBB0_991:
	s_ashr_i32 s31, s30, 31
	s_lshl_b64 s[34:35], s[30:31], 21
	s_add_u32 s34, s74, s34
	v_readlane_b32 s29, v247, 29
	s_addc_u32 s35, s29, s35
	s_and_b64 s[36:37], s[0:1], exec
	s_cselect_b32 s31, s35, s41
	s_cselect_b32 s59, s34, s40
	s_ashr_i32 s29, s28, 31
	s_lshl_b64 s[36:37], s[28:29], 21
	s_add_u32 s36, s76, s36
	s_addc_u32 s37, s77, s37
	s_and_b64 s[44:45], s[0:1], exec
	s_cselect_b32 s29, s37, s43
	s_cselect_b32 s61, s36, s42
	s_add_u32 s40, s40, 0x100080
	s_addc_u32 s41, s41, 0
	s_add_u32 s62, s42, 0x100
	v_mov_b32_e32 v2, 0
	s_addc_u32 s63, s43, 0
	s_mov_b32 s66, -2
	v_mov_b32_e32 v3, v2
	v_mov_b32_e32 v4, v2
	v_mov_b32_e32 v5, v2
	v_mov_b32_e32 v6, v2
	v_mov_b32_e32 v7, v2
	v_mov_b32_e32 v8, v2
	v_mov_b32_e32 v9, v2
	v_mov_b32_e32 v14, v2
	v_mov_b32_e32 v15, v2
	v_mov_b32_e32 v16, v2
	v_mov_b32_e32 v17, v2
	v_mov_b32_e32 v22, v2
	v_mov_b32_e32 v23, v2
	v_mov_b32_e32 v24, v2
	v_mov_b32_e32 v25, v2
	v_mov_b32_e32 v30, v2
	v_mov_b32_e32 v31, v2
	v_mov_b32_e32 v32, v2
	v_mov_b32_e32 v33, v2
	v_mov_b32_e32 v38, v2
	v_mov_b32_e32 v39, v2
	v_mov_b32_e32 v40, v2
	v_mov_b32_e32 v41, v2
	v_mov_b32_e32 v46, v2
	v_mov_b32_e32 v47, v2
	v_mov_b32_e32 v48, v2
	v_mov_b32_e32 v49, v2
	v_mov_b32_e32 v54, v2
	v_mov_b32_e32 v55, v2
	v_mov_b32_e32 v56, v2
	v_mov_b32_e32 v57, v2
	v_mov_b32_e32 v10, v2
	v_mov_b32_e32 v11, v2
	v_mov_b32_e32 v12, v2
	v_mov_b32_e32 v13, v2
	v_mov_b32_e32 v18, v2
	v_mov_b32_e32 v19, v2
	v_mov_b32_e32 v20, v2
	v_mov_b32_e32 v21, v2
	v_mov_b32_e32 v26, v2
	v_mov_b32_e32 v27, v2
	v_mov_b32_e32 v28, v2
	v_mov_b32_e32 v29, v2
	v_mov_b32_e32 v34, v2
	v_mov_b32_e32 v35, v2
	v_mov_b32_e32 v36, v2
	v_mov_b32_e32 v37, v2
	v_mov_b32_e32 v42, v2
	v_mov_b32_e32 v43, v2
	v_mov_b32_e32 v44, v2
	v_mov_b32_e32 v45, v2
	v_mov_b32_e32 v50, v2
	v_mov_b32_e32 v51, v2
	v_mov_b32_e32 v52, v2
	v_mov_b32_e32 v53, v2
	v_mov_b32_e32 v58, v2
	v_mov_b32_e32 v59, v2
	v_mov_b32_e32 v60, v2
	v_mov_b32_e32 v61, v2
	v_mov_b32_e32 v62, v2
	v_mov_b32_e32 v63, v2
	v_mov_b32_e32 v64, v2
	v_mov_b32_e32 v65, v2
	v_mov_b32_e32 v66, v2
	v_mov_b32_e32 v67, v2
	v_mov_b32_e32 v68, v2
	v_mov_b32_e32 v69, v2
	v_mov_b32_e32 v70, v2
	v_mov_b32_e32 v71, v2
	v_mov_b32_e32 v72, v2
	v_mov_b32_e32 v73, v2
	v_mov_b32_e32 v78, v2
	v_mov_b32_e32 v79, v2
	v_mov_b32_e32 v80, v2
	v_mov_b32_e32 v81, v2
	v_mov_b32_e32 v86, v2
	v_mov_b32_e32 v87, v2
	v_mov_b32_e32 v88, v2
	v_mov_b32_e32 v89, v2
	v_mov_b32_e32 v94, v2
	v_mov_b32_e32 v95, v2
	v_mov_b32_e32 v96, v2
	v_mov_b32_e32 v97, v2
	v_mov_b32_e32 v102, v2
	v_mov_b32_e32 v103, v2
	v_mov_b32_e32 v104, v2
	v_mov_b32_e32 v105, v2
	v_mov_b32_e32 v110, v2
	v_mov_b32_e32 v111, v2
	v_mov_b32_e32 v112, v2
	v_mov_b32_e32 v113, v2
	v_mov_b32_e32 v118, v2
	v_mov_b32_e32 v119, v2
	v_mov_b32_e32 v120, v2
	v_mov_b32_e32 v121, v2
	v_mov_b32_e32 v74, v2
	v_mov_b32_e32 v75, v2
	v_mov_b32_e32 v76, v2
	v_mov_b32_e32 v77, v2
	v_mov_b32_e32 v82, v2
	v_mov_b32_e32 v83, v2
	v_mov_b32_e32 v84, v2
	v_mov_b32_e32 v85, v2
	v_mov_b32_e32 v90, v2
	v_mov_b32_e32 v91, v2
	v_mov_b32_e32 v92, v2
	v_mov_b32_e32 v93, v2
	v_mov_b32_e32 v98, v2
	v_mov_b32_e32 v99, v2
	v_mov_b32_e32 v100, v2
	v_mov_b32_e32 v101, v2
	v_mov_b32_e32 v106, v2
	v_mov_b32_e32 v107, v2
	v_mov_b32_e32 v108, v2
	v_mov_b32_e32 v109, v2
	v_mov_b32_e32 v114, v2
	v_mov_b32_e32 v115, v2
	v_mov_b32_e32 v116, v2
	v_mov_b32_e32 v117, v2
	v_mov_b32_e32 v122, v2
	v_mov_b32_e32 v123, v2
	v_mov_b32_e32 v124, v2
	v_mov_b32_e32 v125, v2
	v_mov_b32_e32 v126, v2
	v_mov_b32_e32 v127, v2
	v_mov_b32_e32 v128, v2
	v_mov_b32_e32 v129, v2
	s_cmp_lg_u32 s14, 0
	s_cbranch_scc0 .Lmy_p7_trail
.LBB0_992:
	ds_read_b128 v[154:157], v150
	ds_read_b128 v[158:161], v150 offset:1024
	ds_read_b128 v[162:165], v150 offset:2048
	ds_read_b128 v[166:169], v150 offset:3072
	ds_read_b128 v[170:173], v151
	ds_read_b128 v[174:177], v151 offset:1024
	ds_read_b128 v[178:181], v151 offset:2048
	ds_read_b128 v[182:185], v151 offset:3072
	s_add_u32 s42, s40, 0xfff00080
	s_addc_u32 s43, s41, -1
	s_cmp_eq_u32 s66, 60
	s_cselect_b32 s45, s31, s43
	s_cselect_b32 s44, s59, s42
	s_cselect_b32 s43, s29, s63
	s_cselect_b32 s42, s61, s62
	v_lshl_add_u64 v[146:147], s[40:41], 0, v[138:139]
	s_add_i32 m0, s39, 0xc000
	ds_read_b128 v[186:189], v152
	ds_read_b128 v[190:193], v152 offset:1024
	ds_read_b128 v[194:197], v152 offset:2048
	ds_read_b128 v[198:201], v152 offset:3072
	ds_read_b128 v[202:205], v152 offset:4096
	ds_read_b128 v[206:209], v152 offset:5120
	ds_read_b128 v[210:213], v152 offset:6144
	ds_read_b128 v[218:221], v152 offset:7168
	global_load_lds_dwordx4 v[146:147], off
	v_lshl_add_u64 v[146:147], s[40:41], 0, v[140:141]
	s_add_i32 m0, s39, 0xe000
	s_nop 0
	global_load_lds_dwordx4 v[146:147], off
	s_waitcnt vmcnt(8)
	s_waitcnt lgkmcnt(0)
	s_setprio 1
	v_mfma_f32_16x16x32_bf16 v[126:129], v[154:157], v[186:189], v[126:129]
	v_mfma_f32_16x16x32_bf16 v[122:125], v[162:165], v[186:189], v[122:125]
	v_mfma_f32_16x16x32_bf16 v[114:117], v[154:157], v[194:197], v[114:117]
	v_mfma_f32_16x16x32_bf16 v[106:109], v[162:165], v[194:197], v[106:109]
	v_mfma_f32_16x16x32_bf16 v[98:101], v[154:157], v[202:205], v[98:101]
	v_mfma_f32_16x16x32_bf16 v[90:93], v[162:165], v[202:205], v[90:93]
	v_mfma_f32_16x16x32_bf16 v[82:85], v[154:157], v[210:213], v[82:85]
	v_mfma_f32_16x16x32_bf16 v[74:77], v[162:165], v[210:213], v[74:77]
	v_mfma_f32_16x16x32_bf16 v[126:129], v[158:161], v[190:193], v[126:129]
	v_mfma_f32_16x16x32_bf16 v[122:125], v[166:169], v[190:193], v[122:125]
	v_mfma_f32_16x16x32_bf16 v[114:117], v[158:161], v[198:201], v[114:117]
	v_mfma_f32_16x16x32_bf16 v[106:109], v[166:169], v[198:201], v[106:109]
	v_mfma_f32_16x16x32_bf16 v[98:101], v[158:161], v[206:209], v[98:101]
	v_mfma_f32_16x16x32_bf16 v[90:93], v[166:169], v[206:209], v[90:93]
	v_mfma_f32_16x16x32_bf16 v[82:85], v[158:161], v[218:221], v[82:85]
	v_mfma_f32_16x16x32_bf16 v[74:77], v[166:169], v[218:221], v[74:77]
	s_setprio 2
	v_mfma_f32_16x16x32_bf16 v[118:121], v[170:173], v[186:189], v[118:121]
	v_mfma_f32_16x16x32_bf16 v[110:113], v[178:181], v[186:189], v[110:113]
	v_mfma_f32_16x16x32_bf16 v[102:105], v[170:173], v[194:197], v[102:105]
	v_mfma_f32_16x16x32_bf16 v[94:97], v[178:181], v[194:197], v[94:97]
	v_mfma_f32_16x16x32_bf16 v[86:89], v[170:173], v[202:205], v[86:89]
	v_mfma_f32_16x16x32_bf16 v[78:81], v[178:181], v[202:205], v[78:81]
	v_mfma_f32_16x16x32_bf16 v[70:73], v[170:173], v[210:213], v[70:73]
	v_mfma_f32_16x16x32_bf16 v[66:69], v[178:181], v[210:213], v[66:69]
	v_mfma_f32_16x16x32_bf16 v[118:121], v[174:177], v[190:193], v[118:121]
	v_mfma_f32_16x16x32_bf16 v[110:113], v[182:185], v[190:193], v[110:113]
	v_mfma_f32_16x16x32_bf16 v[102:105], v[174:177], v[198:201], v[102:105]
	v_mfma_f32_16x16x32_bf16 v[94:97], v[182:185], v[198:201], v[94:97]
	v_mfma_f32_16x16x32_bf16 v[86:89], v[174:177], v[206:209], v[86:89]
	v_mfma_f32_16x16x32_bf16 v[78:81], v[182:185], v[206:209], v[78:81]
	v_mfma_f32_16x16x32_bf16 v[70:73], v[174:177], v[218:221], v[70:73]
	v_mfma_f32_16x16x32_bf16 v[66:69], v[182:185], v[218:221], v[66:69]
	s_barrier
; #define PG8_STAGE(bufoff, gbase, voff) do { _Pragma("unroll") for (int _i = 0; _i < 2; ++_i) \
;         __builtin_amdgcn_global_load_lds((const unsigned*)((const char*)(gbase) + (voff)[_i]), (PG8_LAS unsigned*)(lds + (bufoff) + ldsw + _i * 8192), 16, 0, 0); } while (0)
; #define PG8_LDA(dst, b, h) do { _Pragma("unroll") for (int m = 0; m < 4; ++m) _Pragma("unroll") for (int k = 0; k < 2; ++k) dst[m][k] = *(const PG8_LAS bf16x8*)(lds + PG8_SA(b, h) + aoff + m * 2048 + k * 1024); } while (0)
; #define PG8_LDB(dst, b, h) do { _Pragma("unroll") for (int n = 0; n < 2; ++n) _Pragma("unroll") for (int k = 0; k < 2; ++k) dst[n][k] = *(const PG8_LAS bf16x8*)(lds + PG8_SB(b, h) + boff + n * 2048 + k * 1024); } while (0)
; #define PG8_MMA(ai, bj, At, Bt) do { __builtin_amdgcn_s_setprio(1); _Pragma("unroll") for (int m = 0; m < 4; ++m) _Pragma("unroll") for (int n = 0; n < 2; ++n) _Pragma("unroll") for (int k = 0; k < 2; ++k) \
;         acc[ai][bj][m][n] = __builtin_amdgcn_mfma_f32_16x16x32_bf16(Bt[n][k], At[m][k], acc[ai][bj][m][n], 0, 0, 0); __builtin_amdgcn_s_setprio(0); } while (0)
; #define PG8_WAIT_V(n) asm volatile("s_waitcnt vmcnt(" #n ")" ::: "memory")
; #define PG8_WAIT_L(n) asm volatile("s_waitcnt lgkmcnt(" #n ")" ::: "memory")
; #define PG8_BAR __builtin_amdgcn_s_barrier()
; #define PG8_SCHED __builtin_amdgcn_sched_barrier(0)
; template <class Epi, class Sched, bool ALIGN_EPI = false, bool SP2 = false>
; __device__ __forceinline__ void gemm_phase(PG8_LAS unsigned char* lds, const Gemm g, const Sched& S, const Epi& E) {
;     ...
;             PG8_LDA(At, 0, 1); PG8_STAGE(PG8_SB(0, 0), b2, voffB); PG8_STAGE(PG8_SB(0, 1), b2 + hstep, voffB); PG8_STAGE(PG8_SA(0, 0), a2, voffA);
;             PG8_WAIT_V(8); PG8_WAIT_L(0); PG8_BAR; PG8_MMA(1, 0, At, B0); PG8_MMA(1, 1, At, B1); PG8_BAR; PG8_SCHED;
;             PG8_LDB(B0, 1, 0); PG8_LDB(B1, 1, 1); PG8_SCHED; PG8_LDA(At, 1, 0); PG8_STAGE(PG8_SA(0, 1), a2 + hstep, voffA);
;             PG8_WAIT_V(8); PG8_WAIT_L(0); PG8_BAR; PG8_MMA(0, 0, At, B0); PG8_MMA(0, 1, At, B1); PG8_BAR; PG8_SCHED;
	s_setprio 0
	s_add_i32 s67, s52, s33
	v_lshl_add_u64 v[146:147], s[42:43], 0, v[132:133]
	s_mov_b32 m0, s67
	ds_read_b128 v[186:189], v152 offset:16384
	ds_read_b128 v[190:193], v152 offset:17408
	ds_read_b128 v[194:197], v152 offset:18432
	ds_read_b128 v[198:201], v152 offset:19456
	ds_read_b128 v[202:205], v152 offset:20480
	ds_read_b128 v[206:209], v152 offset:21504
	ds_read_b128 v[210:213], v152 offset:22528
	ds_read_b128 v[218:221], v152 offset:23552
	global_load_lds_dwordx4 v[146:147], off
	s_add_i32 m0, s67, 0x2000
	s_add_u32 s68, s42, 0x100000
	v_lshl_add_u64 v[214:215], s[42:43], 0, v[136:137]
	s_addc_u32 s69, s43, 0
	s_add_i32 s67, s53, s33
	global_load_lds_dwordx4 v[214:215], off
	v_lshl_add_u64 v[222:223], s[68:69], 0, v[132:133]
	s_mov_b32 m0, s67
	v_lshl_add_u64 v[224:225], s[44:45], 0, v[134:135]
	global_load_lds_dwordx4 v[222:223], off
	v_lshl_add_u64 v[222:223], s[68:69], 0, v[136:137]
	s_add_i32 m0, s67, 0x2000
	s_nop 0
	global_load_lds_dwordx4 v[222:223], off
	v_lshl_add_u64 v[222:223], s[44:45], 0, v[130:131]
	s_mov_b32 m0, s39
	s_nop 0
	global_load_lds_dwordx4 v[222:223], off
	s_mov_b32 m0, s46
	s_nop 0
	global_load_lds_dwordx4 v[224:225], off
	s_waitcnt vmcnt(8)
	s_waitcnt lgkmcnt(0)
	s_setprio 1
	v_mfma_f32_16x16x32_bf16 v[62:65], v[154:157], v[186:189], v[62:65]
	v_mfma_f32_16x16x32_bf16 v[58:61], v[162:165], v[186:189], v[58:61]
	v_mfma_f32_16x16x32_bf16 v[50:53], v[154:157], v[194:197], v[50:53]
	v_mfma_f32_16x16x32_bf16 v[42:45], v[162:165], v[194:197], v[42:45]
	v_mfma_f32_16x16x32_bf16 v[34:37], v[154:157], v[202:205], v[34:37]
	v_mfma_f32_16x16x32_bf16 v[26:29], v[162:165], v[202:205], v[26:29]
	v_mfma_f32_16x16x32_bf16 v[18:21], v[154:157], v[210:213], v[18:21]
	v_mfma_f32_16x16x32_bf16 v[10:13], v[162:165], v[210:213], v[10:13]
	v_mfma_f32_16x16x32_bf16 v[62:65], v[158:161], v[190:193], v[62:65]
	v_mfma_f32_16x16x32_bf16 v[58:61], v[166:169], v[190:193], v[58:61]
	v_mfma_f32_16x16x32_bf16 v[50:53], v[158:161], v[198:201], v[50:53]
	v_mfma_f32_16x16x32_bf16 v[42:45], v[166:169], v[198:201], v[42:45]
	v_mfma_f32_16x16x32_bf16 v[34:37], v[158:161], v[206:209], v[34:37]
	v_mfma_f32_16x16x32_bf16 v[26:29], v[166:169], v[206:209], v[26:29]
	v_mfma_f32_16x16x32_bf16 v[18:21], v[158:161], v[218:221], v[18:21]
	v_mfma_f32_16x16x32_bf16 v[10:13], v[166:169], v[218:221], v[10:13]
	s_setprio 2
	v_mfma_f32_16x16x32_bf16 v[54:57], v[170:173], v[186:189], v[54:57]
	v_mfma_f32_16x16x32_bf16 v[46:49], v[178:181], v[186:189], v[46:49]
	v_mfma_f32_16x16x32_bf16 v[38:41], v[170:173], v[194:197], v[38:41]
	v_mfma_f32_16x16x32_bf16 v[30:33], v[178:181], v[194:197], v[30:33]
	v_mfma_f32_16x16x32_bf16 v[22:25], v[170:173], v[202:205], v[22:25]
	v_mfma_f32_16x16x32_bf16 v[14:17], v[178:181], v[202:205], v[14:17]
	v_mfma_f32_16x16x32_bf16 v[6:9], v[170:173], v[210:213], v[6:9]
	v_mfma_f32_16x16x32_bf16 v[2:5], v[178:181], v[210:213], v[2:5]
	v_mfma_f32_16x16x32_bf16 v[54:57], v[174:177], v[190:193], v[54:57]
	v_mfma_f32_16x16x32_bf16 v[46:49], v[182:185], v[190:193], v[46:49]
	v_mfma_f32_16x16x32_bf16 v[38:41], v[174:177], v[198:201], v[38:41]
	v_mfma_f32_16x16x32_bf16 v[30:33], v[182:185], v[198:201], v[30:33]
	v_mfma_f32_16x16x32_bf16 v[22:25], v[174:177], v[206:209], v[22:25]
	v_mfma_f32_16x16x32_bf16 v[14:17], v[182:185], v[206:209], v[14:17]
	v_mfma_f32_16x16x32_bf16 v[6:9], v[174:177], v[218:221], v[6:9]
	v_mfma_f32_16x16x32_bf16 v[2:5], v[182:185], v[218:221], v[2:5]
	s_barrier
	s_setprio 0
	s_add_i32 s67, 0, 0x18000
	v_add_u32_e32 v153, s67, v148
	s_add_i32 s68, 0, 0x1c000
	ds_read_b128 v[154:157], v153
	ds_read_b128 v[158:161], v153 offset:1024
	ds_read_b128 v[162:165], v153 offset:2048
	ds_read_b128 v[166:169], v153 offset:3072
	v_add_u32_e32 v153, s68, v148
	ds_read_b128 v[170:173], v153
	ds_read_b128 v[174:177], v153 offset:1024
	ds_read_b128 v[178:181], v153 offset:2048
	ds_read_b128 v[182:185], v153 offset:3072
	s_add_u32 s44, s44, 0x100000
	s_addc_u32 s45, s45, 0
	s_mov_b32 m0, s47
	v_lshl_add_u64 v[226:227], s[44:45], 0, v[130:131]
	ds_read_b128 v[186:189], v152 offset:32768
	ds_read_b128 v[190:193], v152 offset:33792
	ds_read_b128 v[194:197], v152 offset:34816
	ds_read_b128 v[198:201], v152 offset:35840
	ds_read_b128 v[202:205], v152 offset:36864
	ds_read_b128 v[206:209], v152 offset:37888
	ds_read_b128 v[210:213], v152 offset:38912
	ds_read_b128 v[218:221], v152 offset:39936
	global_load_lds_dwordx4 v[226:227], off
	v_lshl_add_u64 v[226:227], s[44:45], 0, v[134:135]
	s_mov_b32 m0, s48
	s_nop 0
	global_load_lds_dwordx4 v[226:227], off
	s_waitcnt vmcnt(8)
	s_waitcnt lgkmcnt(0)
	s_setprio 1
	v_mfma_f32_16x16x32_bf16 v[126:129], v[154:157], v[186:189], v[126:129]
	v_mfma_f32_16x16x32_bf16 v[122:125], v[162:165], v[186:189], v[122:125]
	v_mfma_f32_16x16x32_bf16 v[114:117], v[154:157], v[194:197], v[114:117]
	v_mfma_f32_16x16x32_bf16 v[106:109], v[162:165], v[194:197], v[106:109]
	v_mfma_f32_16x16x32_bf16 v[98:101], v[154:157], v[202:205], v[98:101]
	v_mfma_f32_16x16x32_bf16 v[90:93], v[162:165], v[202:205], v[90:93]
	v_mfma_f32_16x16x32_bf16 v[82:85], v[154:157], v[210:213], v[82:85]
	v_mfma_f32_16x16x32_bf16 v[74:77], v[162:165], v[210:213], v[74:77]
	v_mfma_f32_16x16x32_bf16 v[126:129], v[158:161], v[190:193], v[126:129]
	v_mfma_f32_16x16x32_bf16 v[122:125], v[166:169], v[190:193], v[122:125]
	v_mfma_f32_16x16x32_bf16 v[114:117], v[158:161], v[198:201], v[114:117]
	v_mfma_f32_16x16x32_bf16 v[106:109], v[166:169], v[198:201], v[106:109]
	v_mfma_f32_16x16x32_bf16 v[98:101], v[158:161], v[206:209], v[98:101]
	v_mfma_f32_16x16x32_bf16 v[90:93], v[166:169], v[206:209], v[90:93]
	v_mfma_f32_16x16x32_bf16 v[82:85], v[158:161], v[218:221], v[82:85]
	v_mfma_f32_16x16x32_bf16 v[74:77], v[166:169], v[218:221], v[74:77]
	s_setprio 2
	v_mfma_f32_16x16x32_bf16 v[118:121], v[170:173], v[186:189], v[118:121]
	v_mfma_f32_16x16x32_bf16 v[110:113], v[178:181], v[186:189], v[110:113]
	v_mfma_f32_16x16x32_bf16 v[102:105], v[170:173], v[194:197], v[102:105]
	v_mfma_f32_16x16x32_bf16 v[94:97], v[178:181], v[194:197], v[94:97]
	v_mfma_f32_16x16x32_bf16 v[86:89], v[170:173], v[202:205], v[86:89]
	v_mfma_f32_16x16x32_bf16 v[78:81], v[178:181], v[202:205], v[78:81]
	v_mfma_f32_16x16x32_bf16 v[70:73], v[170:173], v[210:213], v[70:73]
	v_mfma_f32_16x16x32_bf16 v[66:69], v[178:181], v[210:213], v[66:69]
	v_mfma_f32_16x16x32_bf16 v[118:121], v[174:177], v[190:193], v[118:121]
	v_mfma_f32_16x16x32_bf16 v[110:113], v[182:185], v[190:193], v[110:113]
	v_mfma_f32_16x16x32_bf16 v[102:105], v[174:177], v[198:201], v[102:105]
	v_mfma_f32_16x16x32_bf16 v[94:97], v[182:185], v[198:201], v[94:97]
	v_mfma_f32_16x16x32_bf16 v[86:89], v[174:177], v[206:209], v[86:89]
	v_mfma_f32_16x16x32_bf16 v[78:81], v[182:185], v[206:209], v[78:81]
	v_mfma_f32_16x16x32_bf16 v[70:73], v[174:177], v[218:221], v[70:73]
	v_mfma_f32_16x16x32_bf16 v[66:69], v[182:185], v[218:221], v[66:69]
	s_barrier
; #define PG8_STAGE(bufoff, gbase, voff) do { _Pragma("unroll") for (int _i = 0; _i < 2; ++_i) \
;         __builtin_amdgcn_global_load_lds((const unsigned*)((const char*)(gbase) + (voff)[_i]), (PG8_LAS unsigned*)(lds + (bufoff) + ldsw + _i * 8192), 16, 0, 0); } while (0)
; #define PG8_LDA(dst, b, h) do { _Pragma("unroll") for (int m = 0; m < 4; ++m) _Pragma("unroll") for (int k = 0; k < 2; ++k) dst[m][k] = *(const PG8_LAS bf16x8*)(lds + PG8_SA(b, h) + aoff + m * 2048 + k * 1024); } while (0)
; #define PG8_LDB(dst, b, h) do { _Pragma("unroll") for (int n = 0; n < 2; ++n) _Pragma("unroll") for (int k = 0; k < 2; ++k) dst[n][k] = *(const PG8_LAS bf16x8*)(lds + PG8_SB(b, h) + boff + n * 2048 + k * 1024); } while (0)
; #define PG8_MMA(ai, bj, At, Bt) do { __builtin_amdgcn_s_setprio(1); _Pragma("unroll") for (int m = 0; m < 4; ++m) _Pragma("unroll") for (int n = 0; n < 2; ++n) _Pragma("unroll") for (int k = 0; k < 2; ++k) \
;         acc[ai][bj][m][n] = __builtin_amdgcn_mfma_f32_16x16x32_bf16(Bt[n][k], At[m][k], acc[ai][bj][m][n], 0, 0, 0); __builtin_amdgcn_s_setprio(0); } while (0)
; #define PG8_WAIT_V(n) asm volatile("s_waitcnt vmcnt(" #n ")" ::: "memory")
; #define PG8_WAIT_L(n) asm volatile("s_waitcnt lgkmcnt(" #n ")" ::: "memory")
; #define PG8_BAR __builtin_amdgcn_s_barrier()
; #define PG8_SCHED __builtin_amdgcn_sched_barrier(0)
; template <class Epi, class Sched, bool ALIGN_EPI = false, bool SP2 = false>
; __device__ __forceinline__ void gemm_phase(PG8_LAS unsigned char* lds, const Gemm g, const Sched& S, const Epi& E) {
;     ...
;             PG8_LDA(At, 1, 1); PG8_STAGE(PG8_SB(1, 0), b3, voffB); PG8_STAGE(PG8_SB(1, 1), b3 + hstep, voffB); PG8_STAGE(PG8_SA(1, 0), a3, voffA);
;             PG8_WAIT_V(8); PG8_WAIT_L(0); PG8_BAR; PG8_MMA(1, 0, At, B0); PG8_MMA(1, 1, At, B1); PG8_BAR; PG8_SCHED;
;             } else {
;             PG8_LDB(B0, 0, 0); PG8_SCHED; PG8_LDA(At, 0, 0); PG8_STAGE(PG8_SA(1, 1), a1 + hstep, voffA);
	s_setprio 0
	s_add_i32 s44, s67, s33
	v_lshl_add_u64 v[146:147], v[146:147], 0, s[12:13]
	s_mov_b32 m0, s44
	ds_read_b128 v[186:189], v152 offset:49152
	ds_read_b128 v[190:193], v152 offset:50176
	ds_read_b128 v[194:197], v152 offset:51200
	ds_read_b128 v[198:201], v152 offset:52224
	ds_read_b128 v[202:205], v152 offset:53248
	ds_read_b128 v[206:209], v152 offset:54272
	ds_read_b128 v[210:213], v152 offset:55296
	ds_read_b128 v[218:221], v152 offset:56320
	global_load_lds_dwordx4 v[146:147], off
	s_add_i32 m0, s44, 0x2000
	s_add_u32 s42, s42, 0x100080
	v_lshl_add_u64 v[146:147], v[214:215], 0, s[12:13]
	s_addc_u32 s43, s43, 0
	s_add_i32 s44, s68, s33
	global_load_lds_dwordx4 v[146:147], off
	v_lshl_add_u64 v[146:147], s[42:43], 0, v[132:133]
	s_mov_b32 m0, s44
	s_nop 0
	global_load_lds_dwordx4 v[146:147], off
	v_lshl_add_u64 v[146:147], s[42:43], 0, v[136:137]
	s_add_i32 m0, s44, 0x2000
	s_nop 0
	global_load_lds_dwordx4 v[146:147], off
	v_lshl_add_u64 v[146:147], v[222:223], 0, s[12:13]
	s_mov_b32 m0, s50
	s_nop 0
	global_load_lds_dwordx4 v[146:147], off
	v_lshl_add_u64 v[146:147], v[224:225], 0, s[12:13]
	s_mov_b32 m0, s51
	s_nop 0
	global_load_lds_dwordx4 v[146:147], off
	s_waitcnt vmcnt(8)
	s_waitcnt lgkmcnt(0)
	s_setprio 1
	v_mfma_f32_16x16x32_bf16 v[62:65], v[154:157], v[186:189], v[62:65]
	v_mfma_f32_16x16x32_bf16 v[58:61], v[162:165], v[186:189], v[58:61]
	v_mfma_f32_16x16x32_bf16 v[50:53], v[154:157], v[194:197], v[50:53]
	v_mfma_f32_16x16x32_bf16 v[42:45], v[162:165], v[194:197], v[42:45]
	v_mfma_f32_16x16x32_bf16 v[34:37], v[154:157], v[202:205], v[34:37]
	v_mfma_f32_16x16x32_bf16 v[26:29], v[162:165], v[202:205], v[26:29]
	v_mfma_f32_16x16x32_bf16 v[18:21], v[154:157], v[210:213], v[18:21]
	v_mfma_f32_16x16x32_bf16 v[10:13], v[162:165], v[210:213], v[10:13]
	v_mfma_f32_16x16x32_bf16 v[62:65], v[158:161], v[190:193], v[62:65]
	v_mfma_f32_16x16x32_bf16 v[58:61], v[166:169], v[190:193], v[58:61]
	v_mfma_f32_16x16x32_bf16 v[50:53], v[158:161], v[198:201], v[50:53]
	v_mfma_f32_16x16x32_bf16 v[42:45], v[166:169], v[198:201], v[42:45]
	v_mfma_f32_16x16x32_bf16 v[34:37], v[158:161], v[206:209], v[34:37]
	v_mfma_f32_16x16x32_bf16 v[26:29], v[166:169], v[206:209], v[26:29]
	v_mfma_f32_16x16x32_bf16 v[18:21], v[158:161], v[218:221], v[18:21]
	v_mfma_f32_16x16x32_bf16 v[10:13], v[166:169], v[218:221], v[10:13]
	s_setprio 2
	v_mfma_f32_16x16x32_bf16 v[54:57], v[170:173], v[186:189], v[54:57]
	v_mfma_f32_16x16x32_bf16 v[46:49], v[178:181], v[186:189], v[46:49]
	v_mfma_f32_16x16x32_bf16 v[38:41], v[170:173], v[194:197], v[38:41]
	v_mfma_f32_16x16x32_bf16 v[30:33], v[178:181], v[194:197], v[30:33]
	v_mfma_f32_16x16x32_bf16 v[22:25], v[170:173], v[202:205], v[22:25]
	v_mfma_f32_16x16x32_bf16 v[14:17], v[178:181], v[202:205], v[14:17]
	v_mfma_f32_16x16x32_bf16 v[6:9], v[170:173], v[210:213], v[6:9]
	v_mfma_f32_16x16x32_bf16 v[2:5], v[178:181], v[210:213], v[2:5]
	v_mfma_f32_16x16x32_bf16 v[54:57], v[174:177], v[190:193], v[54:57]
	v_mfma_f32_16x16x32_bf16 v[46:49], v[182:185], v[190:193], v[46:49]
	v_mfma_f32_16x16x32_bf16 v[38:41], v[174:177], v[198:201], v[38:41]
	v_mfma_f32_16x16x32_bf16 v[30:33], v[182:185], v[198:201], v[30:33]
	v_mfma_f32_16x16x32_bf16 v[22:25], v[174:177], v[206:209], v[22:25]
	v_mfma_f32_16x16x32_bf16 v[14:17], v[182:185], v[206:209], v[14:17]
	v_mfma_f32_16x16x32_bf16 v[6:9], v[174:177], v[218:221], v[6:9]
	v_mfma_f32_16x16x32_bf16 v[2:5], v[182:185], v[218:221], v[2:5]
	s_barrier
	s_setprio 0
	s_add_i32 s66, s66, 2
	s_add_u32 s40, s40, 0x100
	s_addc_u32 s41, s41, 0
	s_add_u32 s62, s62, 0x100
	s_addc_u32 s63, s63, 0
	s_cmp_gt_u32 s66, 61
	s_cbranch_scc0 .LBB0_992
	s_branch .Lmy_p7_kdone
.Lmy_p7_trail:
	ds_read_b128 v[154:157], v150
	ds_read_b128 v[158:161], v150 offset:1024
	ds_read_b128 v[162:165], v150 offset:2048
	ds_read_b128 v[166:169], v150 offset:3072
	ds_read_b128 v[170:173], v151
	ds_read_b128 v[174:177], v151 offset:1024
	ds_read_b128 v[178:181], v151 offset:2048
	ds_read_b128 v[182:185], v151 offset:3072
	s_add_u32 s42, s40, 0xfff00080
	s_addc_u32 s43, s41, -1
	s_cmp_eq_u32 s66, 60
	s_cselect_b32 s45, s31, s43
	s_cselect_b32 s44, s59, s42
	s_cselect_b32 s43, s29, s63
	s_cselect_b32 s42, s61, s62
	v_lshl_add_u64 v[146:147], s[40:41], 0, v[138:139]
	s_add_i32 m0, s39, 0xc000
	ds_read_b128 v[186:189], v152
	ds_read_b128 v[190:193], v152 offset:1024
	ds_read_b128 v[194:197], v152 offset:2048
	ds_read_b128 v[198:201], v152 offset:3072
	ds_read_b128 v[202:205], v152 offset:4096
	ds_read_b128 v[206:209], v152 offset:5120
	ds_read_b128 v[210:213], v152 offset:6144
	ds_read_b128 v[218:221], v152 offset:7168
	global_load_lds_dwordx4 v[146:147], off
	v_lshl_add_u64 v[146:147], s[40:41], 0, v[140:141]
	s_add_i32 m0, s39, 0xe000
	s_nop 0
	global_load_lds_dwordx4 v[146:147], off
	s_waitcnt vmcnt(8)
	s_waitcnt lgkmcnt(0)
	s_setprio 1
	s_barrier
; #define PG8_STAGE(bufoff, gbase, voff) do { _Pragma("unroll") for (int _i = 0; _i < 2; ++_i) \
;         __builtin_amdgcn_global_load_lds((const unsigned*)((const char*)(gbase) + (voff)[_i]), (PG8_LAS unsigned*)(lds + (bufoff) + ldsw + _i * 8192), 16, 0, 0); } while (0)
; #define PG8_LDA(dst, b, h) do { _Pragma("unroll") for (int m = 0; m < 4; ++m) _Pragma("unroll") for (int k = 0; k < 2; ++k) dst[m][k] = *(const PG8_LAS bf16x8*)(lds + PG8_SA(b, h) + aoff + m * 2048 + k * 1024); } while (0)
; #define PG8_LDB(dst, b, h) do { _Pragma("unroll") for (int n = 0; n < 2; ++n) _Pragma("unroll") for (int k = 0; k < 2; ++k) dst[n][k] = *(const PG8_LAS bf16x8*)(lds + PG8_SB(b, h) + boff + n * 2048 + k * 1024); } while (0)
; #define PG8_MMA(ai, bj, At, Bt) do { __builtin_amdgcn_s_setprio(1); _Pragma("unroll") for (int m = 0; m < 4; ++m) _Pragma("unroll") for (int n = 0; n < 2; ++n) _Pragma("unroll") for (int k = 0; k < 2; ++k) \
;         acc[ai][bj][m][n] = __builtin_amdgcn_mfma_f32_16x16x32_bf16(Bt[n][k], At[m][k], acc[ai][bj][m][n], 0, 0, 0); __builtin_amdgcn_s_setprio(0); } while (0)
; #define PG8_WAIT_V(n) asm volatile("s_waitcnt vmcnt(" #n ")" ::: "memory")
; #define PG8_WAIT_L(n) asm volatile("s_waitcnt lgkmcnt(" #n ")" ::: "memory")
; #define PG8_BAR __builtin_amdgcn_s_barrier()
; #define PG8_SCHED __builtin_amdgcn_sched_barrier(0)
; template <class Epi, class Sched, bool ALIGN_EPI = false, bool SP2 = false>
; __device__ __forceinline__ void gemm_phase(PG8_LAS unsigned char* lds, const Gemm g, const Sched& S, const Epi& E) {
;     ...
;             PG8_LDB(B0, 0, 0); PG8_LDB(B1, 0, 1); PG8_SCHED; PG8_LDA(At, 0, 0); PG8_STAGE(PG8_SA(1, 1), a1 + hstep, voffA);
;             PG8_WAIT_V(8); PG8_WAIT_L(0); PG8_BAR; PG8_MMA(0, 0, At, B0); PG8_MMA(0, 1, At, B1); PG8_BAR; PG8_SCHED;
;             PG8_LDA(At, 0, 1); PG8_STAGE(PG8_SB(0, 0), b2, voffB); PG8_STAGE(PG8_SB(0, 1), b2 + hstep, voffB); PG8_STAGE(PG8_SA(0, 0), a2, voffA);
;             PG8_WAIT_V(8); PG8_WAIT_L(0); PG8_BAR; PG8_MMA(1, 0, At, B0); PG8_MMA(1, 1, At, B1); PG8_BAR; PG8_SCHED;
;             PG8_LDB(B0, 1, 0); PG8_LDB(B1, 1, 1); PG8_SCHED; PG8_LDA(At, 1, 0); PG8_STAGE(PG8_SA(0, 1), a2 + hstep, voffA);
;             PG8_WAIT_V(8); PG8_WAIT_L(0); PG8_BAR; PG8_MMA(0, 0, At, B0); PG8_MMA(0, 1, At, B1); PG8_BAR; PG8_SCHED;
	v_mfma_f32_16x16x32_bf16 v[126:129], v[154:157], v[186:189], v[126:129]
	v_mfma_f32_16x16x32_bf16 v[122:125], v[162:165], v[186:189], v[122:125]
	v_mfma_f32_16x16x32_bf16 v[114:117], v[154:157], v[194:197], v[114:117]
	v_mfma_f32_16x16x32_bf16 v[106:109], v[162:165], v[194:197], v[106:109]
	v_mfma_f32_16x16x32_bf16 v[98:101], v[154:157], v[202:205], v[98:101]
	v_mfma_f32_16x16x32_bf16 v[90:93], v[162:165], v[202:205], v[90:93]
	v_mfma_f32_16x16x32_bf16 v[82:85], v[154:157], v[210:213], v[82:85]
	v_mfma_f32_16x16x32_bf16 v[74:77], v[162:165], v[210:213], v[74:77]
	v_mfma_f32_16x16x32_bf16 v[126:129], v[158:161], v[190:193], v[126:129]
	v_mfma_f32_16x16x32_bf16 v[122:125], v[166:169], v[190:193], v[122:125]
	v_mfma_f32_16x16x32_bf16 v[114:117], v[158:161], v[198:201], v[114:117]
	v_mfma_f32_16x16x32_bf16 v[106:109], v[166:169], v[198:201], v[106:109]
	v_mfma_f32_16x16x32_bf16 v[98:101], v[158:161], v[206:209], v[98:101]
	v_mfma_f32_16x16x32_bf16 v[90:93], v[166:169], v[206:209], v[90:93]
	v_mfma_f32_16x16x32_bf16 v[82:85], v[158:161], v[218:221], v[82:85]
	v_mfma_f32_16x16x32_bf16 v[74:77], v[166:169], v[218:221], v[74:77]
	s_setprio 2
	v_mfma_f32_16x16x32_bf16 v[118:121], v[170:173], v[186:189], v[118:121]
	v_mfma_f32_16x16x32_bf16 v[110:113], v[178:181], v[186:189], v[110:113]
	v_mfma_f32_16x16x32_bf16 v[102:105], v[170:173], v[194:197], v[102:105]
	v_mfma_f32_16x16x32_bf16 v[94:97], v[178:181], v[194:197], v[94:97]
	v_mfma_f32_16x16x32_bf16 v[86:89], v[170:173], v[202:205], v[86:89]
	v_mfma_f32_16x16x32_bf16 v[78:81], v[178:181], v[202:205], v[78:81]
	v_mfma_f32_16x16x32_bf16 v[70:73], v[170:173], v[210:213], v[70:73]
	v_mfma_f32_16x16x32_bf16 v[66:69], v[178:181], v[210:213], v[66:69]
	v_mfma_f32_16x16x32_bf16 v[118:121], v[174:177], v[190:193], v[118:121]
	v_mfma_f32_16x16x32_bf16 v[110:113], v[182:185], v[190:193], v[110:113]
	v_mfma_f32_16x16x32_bf16 v[102:105], v[174:177], v[198:201], v[102:105]
	v_mfma_f32_16x16x32_bf16 v[94:97], v[182:185], v[198:201], v[94:97]
	v_mfma_f32_16x16x32_bf16 v[86:89], v[174:177], v[206:209], v[86:89]
	v_mfma_f32_16x16x32_bf16 v[78:81], v[182:185], v[206:209], v[78:81]
	v_mfma_f32_16x16x32_bf16 v[70:73], v[174:177], v[218:221], v[70:73]
	v_mfma_f32_16x16x32_bf16 v[66:69], v[182:185], v[218:221], v[66:69]
	s_setprio 0
	s_add_i32 s67, s52, s33
	v_lshl_add_u64 v[146:147], s[42:43], 0, v[132:133]
	s_mov_b32 m0, s67
	ds_read_b128 v[186:189], v152 offset:16384
	ds_read_b128 v[190:193], v152 offset:17408
	ds_read_b128 v[194:197], v152 offset:18432
	ds_read_b128 v[198:201], v152 offset:19456
	ds_read_b128 v[202:205], v152 offset:20480
	ds_read_b128 v[206:209], v152 offset:21504
	ds_read_b128 v[210:213], v152 offset:22528
	ds_read_b128 v[218:221], v152 offset:23552
	global_load_lds_dwordx4 v[146:147], off
	s_add_i32 m0, s67, 0x2000
	s_add_u32 s68, s42, 0x100000
	v_lshl_add_u64 v[214:215], s[42:43], 0, v[136:137]
	s_addc_u32 s69, s43, 0
	s_add_i32 s67, s53, s33
	global_load_lds_dwordx4 v[214:215], off
	v_lshl_add_u64 v[222:223], s[68:69], 0, v[132:133]
	s_mov_b32 m0, s67
	v_lshl_add_u64 v[224:225], s[44:45], 0, v[134:135]
	global_load_lds_dwordx4 v[222:223], off
	v_lshl_add_u64 v[222:223], s[68:69], 0, v[136:137]
	s_add_i32 m0, s67, 0x2000
	s_nop 0
	global_load_lds_dwordx4 v[222:223], off
	v_lshl_add_u64 v[222:223], s[44:45], 0, v[130:131]
	s_mov_b32 m0, s39
	s_nop 0
	global_load_lds_dwordx4 v[222:223], off
	s_mov_b32 m0, s46
	s_nop 0
	global_load_lds_dwordx4 v[224:225], off
	s_waitcnt vmcnt(8)
	s_waitcnt lgkmcnt(0)
	s_setprio 1
	s_barrier
	v_mfma_f32_16x16x32_bf16 v[62:65], v[154:157], v[186:189], v[62:65]
	v_mfma_f32_16x16x32_bf16 v[58:61], v[162:165], v[186:189], v[58:61]
	v_mfma_f32_16x16x32_bf16 v[50:53], v[154:157], v[194:197], v[50:53]
	v_mfma_f32_16x16x32_bf16 v[42:45], v[162:165], v[194:197], v[42:45]
	v_mfma_f32_16x16x32_bf16 v[34:37], v[154:157], v[202:205], v[34:37]
	v_mfma_f32_16x16x32_bf16 v[26:29], v[162:165], v[202:205], v[26:29]
	v_mfma_f32_16x16x32_bf16 v[18:21], v[154:157], v[210:213], v[18:21]
	v_mfma_f32_16x16x32_bf16 v[10:13], v[162:165], v[210:213], v[10:13]
	v_mfma_f32_16x16x32_bf16 v[62:65], v[158:161], v[190:193], v[62:65]
	v_mfma_f32_16x16x32_bf16 v[58:61], v[166:169], v[190:193], v[58:61]
	v_mfma_f32_16x16x32_bf16 v[50:53], v[158:161], v[198:201], v[50:53]
	v_mfma_f32_16x16x32_bf16 v[42:45], v[166:169], v[198:201], v[42:45]
	v_mfma_f32_16x16x32_bf16 v[34:37], v[158:161], v[206:209], v[34:37]
	v_mfma_f32_16x16x32_bf16 v[26:29], v[166:169], v[206:209], v[26:29]
	v_mfma_f32_16x16x32_bf16 v[18:21], v[158:161], v[218:221], v[18:21]
	v_mfma_f32_16x16x32_bf16 v[10:13], v[166:169], v[218:221], v[10:13]
	s_setprio 2
	v_mfma_f32_16x16x32_bf16 v[54:57], v[170:173], v[186:189], v[54:57]
	v_mfma_f32_16x16x32_bf16 v[46:49], v[178:181], v[186:189], v[46:49]
	v_mfma_f32_16x16x32_bf16 v[38:41], v[170:173], v[194:197], v[38:41]
	v_mfma_f32_16x16x32_bf16 v[30:33], v[178:181], v[194:197], v[30:33]
	v_mfma_f32_16x16x32_bf16 v[22:25], v[170:173], v[202:205], v[22:25]
	v_mfma_f32_16x16x32_bf16 v[14:17], v[178:181], v[202:205], v[14:17]
	v_mfma_f32_16x16x32_bf16 v[6:9], v[170:173], v[210:213], v[6:9]
	v_mfma_f32_16x16x32_bf16 v[2:5], v[178:181], v[210:213], v[2:5]
	v_mfma_f32_16x16x32_bf16 v[54:57], v[174:177], v[190:193], v[54:57]
	v_mfma_f32_16x16x32_bf16 v[46:49], v[182:185], v[190:193], v[46:49]
	v_mfma_f32_16x16x32_bf16 v[38:41], v[174:177], v[198:201], v[38:41]
	v_mfma_f32_16x16x32_bf16 v[30:33], v[182:185], v[198:201], v[30:33]
	v_mfma_f32_16x16x32_bf16 v[22:25], v[174:177], v[206:209], v[22:25]
	v_mfma_f32_16x16x32_bf16 v[14:17], v[182:185], v[206:209], v[14:17]
	v_mfma_f32_16x16x32_bf16 v[6:9], v[174:177], v[218:221], v[6:9]
	v_mfma_f32_16x16x32_bf16 v[2:5], v[182:185], v[218:221], v[2:5]
	s_setprio 0
	s_add_i32 s67, 0, 0x18000
	v_add_u32_e32 v153, s67, v148
	s_add_i32 s68, 0, 0x1c000
	ds_read_b128 v[154:157], v153
	ds_read_b128 v[158:161], v153 offset:1024
	ds_read_b128 v[162:165], v153 offset:2048
	ds_read_b128 v[166:169], v153 offset:3072
	v_add_u32_e32 v153, s68, v148
	ds_read_b128 v[170:173], v153
	ds_read_b128 v[174:177], v153 offset:1024
	ds_read_b128 v[178:181], v153 offset:2048
	ds_read_b128 v[182:185], v153 offset:3072
	s_add_u32 s44, s44, 0x100000
	s_addc_u32 s45, s45, 0
	s_mov_b32 m0, s47
	v_lshl_add_u64 v[226:227], s[44:45], 0, v[130:131]
	ds_read_b128 v[186:189], v152 offset:32768
	ds_read_b128 v[190:193], v152 offset:33792
	ds_read_b128 v[194:197], v152 offset:34816
	ds_read_b128 v[198:201], v152 offset:35840
	ds_read_b128 v[202:205], v152 offset:36864
	ds_read_b128 v[206:209], v152 offset:37888
	ds_read_b128 v[210:213], v152 offset:38912
	ds_read_b128 v[218:221], v152 offset:39936
	global_load_lds_dwordx4 v[226:227], off
	v_lshl_add_u64 v[226:227], s[44:45], 0, v[134:135]
	s_mov_b32 m0, s48
	s_nop 0
	global_load_lds_dwordx4 v[226:227], off
	s_waitcnt vmcnt(8)
	s_waitcnt lgkmcnt(0)
	s_setprio 1
	s_barrier
; #define PG8_STAGE(bufoff, gbase, voff) do { _Pragma("unroll") for (int _i = 0; _i < 2; ++_i) \
;         __builtin_amdgcn_global_load_lds((const unsigned*)((const char*)(gbase) + (voff)[_i]), (PG8_LAS unsigned*)(lds + (bufoff) + ldsw + _i * 8192), 16, 0, 0); } while (0)
; #define PG8_LDA(dst, b, h) do { _Pragma("unroll") for (int m = 0; m < 4; ++m) _Pragma("unroll") for (int k = 0; k < 2; ++k) dst[m][k] = *(const PG8_LAS bf16x8*)(lds + PG8_SA(b, h) + aoff + m * 2048 + k * 1024); } while (0)
; #define PG8_LDB(dst, b, h) do { _Pragma("unroll") for (int n = 0; n < 2; ++n) _Pragma("unroll") for (int k = 0; k < 2; ++k) dst[n][k] = *(const PG8_LAS bf16x8*)(lds + PG8_SB(b, h) + boff + n * 2048 + k * 1024); } while (0)
; #define PG8_MMA(ai, bj, At, Bt) do { __builtin_amdgcn_s_setprio(1); _Pragma("unroll") for (int m = 0; m < 4; ++m) _Pragma("unroll") for (int n = 0; n < 2; ++n) _Pragma("unroll") for (int k = 0; k < 2; ++k) \
;         acc[ai][bj][m][n] = __builtin_amdgcn_mfma_f32_16x16x32_bf16(Bt[n][k], At[m][k], acc[ai][bj][m][n], 0, 0, 0); __builtin_amdgcn_s_setprio(0); } while (0)
; #define PG8_WAIT_V(n) asm volatile("s_waitcnt vmcnt(" #n ")" ::: "memory")
; #define PG8_WAIT_L(n) asm volatile("s_waitcnt lgkmcnt(" #n ")" ::: "memory")
; #define PG8_BAR __builtin_amdgcn_s_barrier()
; template <class Epi, class Sched, bool ALIGN_EPI = false, bool SP2 = false>
; __device__ __forceinline__ void gemm_phase(PG8_LAS unsigned char* lds, const Gemm g, const Sched& S, const Epi& E) {
;     ...
;         for (int t = 0; t < nt; t += 2) {
;             const bool last = (t == nt - 2);
;             const char* a1 = cA + (size_t)(t + 1) * kstep;
;             const char* a2 = last ? nA : cA + (size_t)(t + 2) * kstep; const char* b2 = last ? nB : cB + (size_t)(t + 2) * kstep;
;             const char* a3 = a2 + kstep; const char* b3 = b2 + kstep;
;     ...
;             PG8_LDB(B0, 1, 0); PG8_LDB(B1, 1, 1); PG8_SCHED; PG8_LDA(At, 1, 0); PG8_STAGE(PG8_SA(0, 1), a2 + hstep, voffA);
;             PG8_WAIT_V(8); PG8_WAIT_L(0); PG8_BAR; PG8_MMA(0, 0, At, B0); PG8_MMA(0, 1, At, B1); PG8_BAR; PG8_SCHED;
;             PG8_LDA(At, 1, 1); PG8_STAGE(PG8_SB(1, 0), b3, voffB); PG8_STAGE(PG8_SB(1, 1), b3 + hstep, voffB); PG8_STAGE(PG8_SA(1, 0), a3, voffA);
;             PG8_WAIT_V(8); PG8_WAIT_L(0); PG8_BAR; PG8_MMA(1, 0, At, B0); PG8_MMA(1, 1, At, B1); PG8_BAR; PG8_SCHED;
	v_mfma_f32_16x16x32_bf16 v[126:129], v[154:157], v[186:189], v[126:129]
	v_mfma_f32_16x16x32_bf16 v[122:125], v[162:165], v[186:189], v[122:125]
	v_mfma_f32_16x16x32_bf16 v[114:117], v[154:157], v[194:197], v[114:117]
	v_mfma_f32_16x16x32_bf16 v[106:109], v[162:165], v[194:197], v[106:109]
	v_mfma_f32_16x16x32_bf16 v[98:101], v[154:157], v[202:205], v[98:101]
	v_mfma_f32_16x16x32_bf16 v[90:93], v[162:165], v[202:205], v[90:93]
	v_mfma_f32_16x16x32_bf16 v[82:85], v[154:157], v[210:213], v[82:85]
	v_mfma_f32_16x16x32_bf16 v[74:77], v[162:165], v[210:213], v[74:77]
	v_mfma_f32_16x16x32_bf16 v[126:129], v[158:161], v[190:193], v[126:129]
	v_mfma_f32_16x16x32_bf16 v[122:125], v[166:169], v[190:193], v[122:125]
	v_mfma_f32_16x16x32_bf16 v[114:117], v[158:161], v[198:201], v[114:117]
	v_mfma_f32_16x16x32_bf16 v[106:109], v[166:169], v[198:201], v[106:109]
	v_mfma_f32_16x16x32_bf16 v[98:101], v[158:161], v[206:209], v[98:101]
	v_mfma_f32_16x16x32_bf16 v[90:93], v[166:169], v[206:209], v[90:93]
	v_mfma_f32_16x16x32_bf16 v[82:85], v[158:161], v[218:221], v[82:85]
	v_mfma_f32_16x16x32_bf16 v[74:77], v[166:169], v[218:221], v[74:77]
	s_setprio 2
	v_mfma_f32_16x16x32_bf16 v[118:121], v[170:173], v[186:189], v[118:121]
	v_mfma_f32_16x16x32_bf16 v[110:113], v[178:181], v[186:189], v[110:113]
	v_mfma_f32_16x16x32_bf16 v[102:105], v[170:173], v[194:197], v[102:105]
	v_mfma_f32_16x16x32_bf16 v[94:97], v[178:181], v[194:197], v[94:97]
	v_mfma_f32_16x16x32_bf16 v[86:89], v[170:173], v[202:205], v[86:89]
	v_mfma_f32_16x16x32_bf16 v[78:81], v[178:181], v[202:205], v[78:81]
	v_mfma_f32_16x16x32_bf16 v[70:73], v[170:173], v[210:213], v[70:73]
	v_mfma_f32_16x16x32_bf16 v[66:69], v[178:181], v[210:213], v[66:69]
	v_mfma_f32_16x16x32_bf16 v[118:121], v[174:177], v[190:193], v[118:121]
	v_mfma_f32_16x16x32_bf16 v[110:113], v[182:185], v[190:193], v[110:113]
	v_mfma_f32_16x16x32_bf16 v[102:105], v[174:177], v[198:201], v[102:105]
	v_mfma_f32_16x16x32_bf16 v[94:97], v[182:185], v[198:201], v[94:97]
	v_mfma_f32_16x16x32_bf16 v[86:89], v[174:177], v[206:209], v[86:89]
	v_mfma_f32_16x16x32_bf16 v[78:81], v[182:185], v[206:209], v[78:81]
	v_mfma_f32_16x16x32_bf16 v[70:73], v[174:177], v[218:221], v[70:73]
	v_mfma_f32_16x16x32_bf16 v[66:69], v[182:185], v[218:221], v[66:69]
	s_setprio 0
	s_add_i32 s44, s67, s33
	v_lshl_add_u64 v[146:147], v[146:147], 0, s[12:13]
	s_mov_b32 m0, s44
	ds_read_b128 v[186:189], v152 offset:49152
	ds_read_b128 v[190:193], v152 offset:50176
	ds_read_b128 v[194:197], v152 offset:51200
	ds_read_b128 v[198:201], v152 offset:52224
	ds_read_b128 v[202:205], v152 offset:53248
	ds_read_b128 v[206:209], v152 offset:54272
	ds_read_b128 v[210:213], v152 offset:55296
	ds_read_b128 v[218:221], v152 offset:56320
	global_load_lds_dwordx4 v[146:147], off
	s_add_i32 m0, s44, 0x2000
	s_add_u32 s42, s42, 0x100080
	v_lshl_add_u64 v[146:147], v[214:215], 0, s[12:13]
	s_addc_u32 s43, s43, 0
	s_add_i32 s44, s68, s33
	global_load_lds_dwordx4 v[146:147], off
	v_lshl_add_u64 v[146:147], s[42:43], 0, v[132:133]
	s_mov_b32 m0, s44
	s_nop 0
	global_load_lds_dwordx4 v[146:147], off
	v_lshl_add_u64 v[146:147], s[42:43], 0, v[136:137]
	s_add_i32 m0, s44, 0x2000
	s_nop 0
	global_load_lds_dwordx4 v[146:147], off
	v_lshl_add_u64 v[146:147], v[222:223], 0, s[12:13]
	s_mov_b32 m0, s50
	s_nop 0
	global_load_lds_dwordx4 v[146:147], off
	v_lshl_add_u64 v[146:147], v[224:225], 0, s[12:13]
	s_mov_b32 m0, s51
	s_nop 0
	global_load_lds_dwordx4 v[146:147], off
	s_waitcnt vmcnt(8)
	s_waitcnt lgkmcnt(0)
	s_setprio 1
	s_barrier
	v_mfma_f32_16x16x32_bf16 v[62:65], v[154:157], v[186:189], v[62:65]
	v_mfma_f32_16x16x32_bf16 v[58:61], v[162:165], v[186:189], v[58:61]
	v_mfma_f32_16x16x32_bf16 v[50:53], v[154:157], v[194:197], v[50:53]
	v_mfma_f32_16x16x32_bf16 v[42:45], v[162:165], v[194:197], v[42:45]
	v_mfma_f32_16x16x32_bf16 v[34:37], v[154:157], v[202:205], v[34:37]
	v_mfma_f32_16x16x32_bf16 v[26:29], v[162:165], v[202:205], v[26:29]
	v_mfma_f32_16x16x32_bf16 v[18:21], v[154:157], v[210:213], v[18:21]
	v_mfma_f32_16x16x32_bf16 v[10:13], v[162:165], v[210:213], v[10:13]
	v_mfma_f32_16x16x32_bf16 v[62:65], v[158:161], v[190:193], v[62:65]
	v_mfma_f32_16x16x32_bf16 v[58:61], v[166:169], v[190:193], v[58:61]
	v_mfma_f32_16x16x32_bf16 v[50:53], v[158:161], v[198:201], v[50:53]
	v_mfma_f32_16x16x32_bf16 v[42:45], v[166:169], v[198:201], v[42:45]
	v_mfma_f32_16x16x32_bf16 v[34:37], v[158:161], v[206:209], v[34:37]
	v_mfma_f32_16x16x32_bf16 v[26:29], v[166:169], v[206:209], v[26:29]
	v_mfma_f32_16x16x32_bf16 v[18:21], v[158:161], v[218:221], v[18:21]
	v_mfma_f32_16x16x32_bf16 v[10:13], v[166:169], v[218:221], v[10:13]
	s_setprio 2
	v_mfma_f32_16x16x32_bf16 v[54:57], v[170:173], v[186:189], v[54:57]
	v_mfma_f32_16x16x32_bf16 v[46:49], v[178:181], v[186:189], v[46:49]
	v_mfma_f32_16x16x32_bf16 v[38:41], v[170:173], v[194:197], v[38:41]
	v_mfma_f32_16x16x32_bf16 v[30:33], v[178:181], v[194:197], v[30:33]
	v_mfma_f32_16x16x32_bf16 v[22:25], v[170:173], v[202:205], v[22:25]
	v_mfma_f32_16x16x32_bf16 v[14:17], v[178:181], v[202:205], v[14:17]
	v_mfma_f32_16x16x32_bf16 v[6:9], v[170:173], v[210:213], v[6:9]
	v_mfma_f32_16x16x32_bf16 v[2:5], v[178:181], v[210:213], v[2:5]
	v_mfma_f32_16x16x32_bf16 v[54:57], v[174:177], v[190:193], v[54:57]
	v_mfma_f32_16x16x32_bf16 v[46:49], v[182:185], v[190:193], v[46:49]
	v_mfma_f32_16x16x32_bf16 v[38:41], v[174:177], v[198:201], v[38:41]
	v_mfma_f32_16x16x32_bf16 v[30:33], v[182:185], v[198:201], v[30:33]
	v_mfma_f32_16x16x32_bf16 v[22:25], v[174:177], v[206:209], v[22:25]
	v_mfma_f32_16x16x32_bf16 v[14:17], v[182:185], v[206:209], v[14:17]
	v_mfma_f32_16x16x32_bf16 v[6:9], v[174:177], v[218:221], v[6:9]
	v_mfma_f32_16x16x32_bf16 v[2:5], v[182:185], v[218:221], v[2:5]
	s_setprio 0
	s_add_i32 s66, s66, 2
	s_add_u32 s40, s40, 0x100
	s_addc_u32 s41, s41, 0
	s_add_u32 s62, s62, 0x100
	s_addc_u32 s63, s63, 0
	s_cmp_gt_u32 s66, 61
	s_cbranch_scc0 .Lmy_p7_trail
; __device__ __forceinline__ unsigned cvt_pk_bf16(float lo, float hi) { unsigned r; asm volatile("v_cvt_pk_bf16_f32 %0, %1, %2" : "=v"(r) : "v"(lo), "v"(hi)); return r; }
; #define PG8_BAR __builtin_amdgcn_s_barrier()
; template <int ACT> __device__ __forceinline__ f32x4 act4(f32x4 v, float sc) {
;     ...
;     { f32x4 o;
; #pragma unroll
;         for (int j = 0; j < 4; ++j) { const float t = v[j] > 0.f ? v[j] : 0.f; o[j] = t * t; }
;         return o; }
; }
; template <int ACT, int STAT> __device__ __forceinline__ void store_tile(const f32x4 (&acc)[2][2][4][2], bf16_t* base, int ldc, int row0, int col0, float sc, float* stat, int slot, int fq) {
; #pragma unroll
;     for (int ai = 0; ai < 2; ++ai)
; #pragma unroll
;         for (int m = 0; m < 4; ++m) { const int row = row0 + ai * HALF + m * 16; bf16_t* rowp = base + (size_t)row * ldc + col0; float s1 = 0.f, s2 = 0.f;
; #pragma unroll
;             for (int bj = 0; bj < 2; ++bj) { const f32x4 v0 = act4<ACT>(acc[ai][bj][m][0], sc), v1 = act4<ACT>(acc[ai][bj][m][1], sc);
;                 if (STAT) { s1 += (v0[0] + v0[1]) + (v0[2] + v0[3]) + (v1[0] + v1[1]) + (v1[2] + v1[3]);
;                             s2 += (v0[0] * v0[0] + v0[1] * v0[1]) + (v0[2] * v0[2] + v0[3] * v0[3]) + (v1[0] * v1[0] + v1[1] * v1[1]) + (v1[2] * v1[2] + v1[3] * v1[3]); }
;                 u32x4 w; w.x = cvt_pk_bf16(v0[0], v0[1]); w.y = cvt_pk_bf16(v0[2], v0[3]); w.z = cvt_pk_bf16(v1[0], v1[1]); w.w = cvt_pk_bf16(v1[2], v1[3]);
;                 *(u32x4*)(rowp + bj * HALF) = w; }
; template <class Epi, class Sched, bool ALIGN_EPI = false, bool SP2 = false>
; __device__ __forceinline__ void gemm_phase(PG8_LAS unsigned char* lds, const Gemm g, const Sched& S, const Epi& E) {
;     ...
;         if constexpr (ALIGN_EPI) { if (wr == 0) PG8_BAR; }
;         if constexpr (!Epi::AFTER_DRAIN) { E(acc, cur, wr, wc, fr, fq); S.done(cur); }
.Lmy_p7_kdone:
	s_and_b64 vcc, exec, s[14:15]
	s_barrier
.LBB0_995:
	v_max_f32_e32 v122, v122, v122
	v_max_f32_e32 v122, 0, v122
	v_lshl_add_u32 v154, s38, 8, v1
	v_lshl_or_b32 v146, s58, 8, v149
	v_mul_f32_e32 v153, v122, v122
	v_max_f32_e32 v122, v123, v123
	v_ashrrev_i32_e32 v147, 31, v146
	v_ashrrev_i32_e32 v155, 31, v154
	v_max_f32_e32 v122, 0, v122
	v_lshl_add_u64 v[156:157], v[146:147], 1, s[80:81]
	v_lshlrev_b64 v[146:147], 15, v[154:155]
	v_mul_f32_e32 v155, v122, v122
	v_max_f32_e32 v122, v124, v124
	v_max_f32_e32 v122, 0, v122
	v_max_f32_e32 v126, v126, v126
	v_max_f32_e32 v127, v127, v127
	v_mul_f32_e32 v158, v122, v122
	v_max_f32_e32 v122, v125, v125
	v_max_f32_e32 v126, 0, v126
	v_max_f32_e32 v127, 0, v127
	v_max_f32_e32 v128, v128, v128
	v_max_f32_e32 v129, v129, v129
	v_max_f32_e32 v122, 0, v122
	v_max_f32_e32 v110, v110, v110
	v_lshl_add_u64 v[146:147], v[156:157], 0, v[146:147]
	v_mul_f32_e32 v126, v126, v126
	v_mul_f32_e32 v127, v127, v127
	v_max_f32_e32 v128, 0, v128
	v_max_f32_e32 v129, 0, v129
	v_mul_f32_e32 v125, v122, v122
	v_cvt_pk_bf16_f32 v122, v126, v127
	v_max_f32_e32 v110, 0, v110
	v_mul_f32_e32 v128, v128, v128
	v_mul_f32_e32 v129, v129, v129
	v_cvt_pk_bf16_f32 v123, v128, v129
	v_cvt_pk_bf16_f32 v124, v153, v155
	v_cvt_pk_bf16_f32 v125, v158, v125
	global_store_dwordx4 v[146:147], v[122:125], off
	v_max_f32_e32 v118, v118, v118
	v_max_f32_e32 v119, v119, v119
	v_mul_f32_e32 v122, v110, v110
	v_max_f32_e32 v110, v111, v111
	v_max_f32_e32 v110, 0, v110
	v_mul_f32_e32 v123, v110, v110
	v_max_f32_e32 v110, v112, v112
	v_max_f32_e32 v110, 0, v110
	v_max_f32_e32 v120, v120, v120
	v_max_f32_e32 v121, v121, v121
	v_mul_f32_e32 v124, v110, v110
	v_max_f32_e32 v110, v113, v113
	v_max_f32_e32 v118, 0, v118
	v_max_f32_e32 v119, 0, v119
	v_max_f32_e32 v120, 0, v120
	v_max_f32_e32 v121, 0, v121
	v_max_f32_e32 v110, 0, v110
	v_max_f32_e32 v106, v106, v106
	v_mul_f32_e32 v118, v118, v118
	v_mul_f32_e32 v119, v119, v119
	v_mul_f32_e32 v120, v120, v120
	v_mul_f32_e32 v121, v121, v121
	v_mul_f32_e32 v113, v110, v110
	v_cvt_pk_bf16_f32 v110, v118, v119
	v_cvt_pk_bf16_f32 v111, v120, v121
	v_cvt_pk_bf16_f32 v112, v122, v123
	v_max_f32_e32 v106, 0, v106
	v_cvt_pk_bf16_f32 v113, v124, v113
	global_store_dwordx4 v[146:147], v[110:113], off offset:256
	v_max_f32_e32 v94, v94, v94
	v_max_f32_e32 v94, 0, v94
	v_max_f32_e32 v112, v114, v114
	v_max_f32_e32 v114, v116, v116
	v_mul_f32_e32 v116, v106, v106
	v_max_f32_e32 v106, v107, v107
	v_max_f32_e32 v106, 0, v106
	v_max_f32_e32 v113, v115, v115
	v_max_f32_e32 v115, v117, v117
	v_mul_f32_e32 v117, v106, v106
	v_max_f32_e32 v106, v108, v108
	v_or_b32_e32 v110, 16, v154
	v_max_f32_e32 v106, 0, v106
	v_ashrrev_i32_e32 v111, 31, v110
	v_mul_f32_e32 v118, v106, v106
	v_max_f32_e32 v106, v109, v109
	v_lshlrev_b64 v[110:111], 15, v[110:111]
	v_max_f32_e32 v112, 0, v112
	v_max_f32_e32 v113, 0, v113
	v_max_f32_e32 v106, 0, v106
	v_lshl_add_u64 v[110:111], v[156:157], 0, v[110:111]
	v_mul_f32_e32 v112, v112, v112
	v_mul_f32_e32 v113, v113, v113
	v_max_f32_e32 v114, 0, v114
	v_max_f32_e32 v115, 0, v115
	v_mul_f32_e32 v109, v106, v106
	v_cvt_pk_bf16_f32 v106, v112, v113
	v_mul_f32_e32 v114, v114, v114
	v_mul_f32_e32 v115, v115, v115
	v_cvt_pk_bf16_f32 v107, v114, v115
	v_cvt_pk_bf16_f32 v108, v116, v117
	v_cvt_pk_bf16_f32 v109, v118, v109
	global_store_dwordx4 v[110:111], v[106:109], off
	v_max_f32_e32 v102, v102, v102
	v_max_f32_e32 v103, v103, v103
	v_mul_f32_e32 v106, v94, v94
	v_max_f32_e32 v94, v95, v95
	v_max_f32_e32 v94, 0, v94
	v_mul_f32_e32 v107, v94, v94
	v_max_f32_e32 v94, v96, v96
	v_max_f32_e32 v94, 0, v94
	v_max_f32_e32 v104, v104, v104
	v_max_f32_e32 v105, v105, v105
	v_mul_f32_e32 v108, v94, v94
	v_max_f32_e32 v94, v97, v97
	v_max_f32_e32 v102, 0, v102
	v_max_f32_e32 v103, 0, v103
	v_max_f32_e32 v104, 0, v104
	v_max_f32_e32 v105, 0, v105
	v_max_f32_e32 v94, 0, v94
	v_max_f32_e32 v90, v90, v90
	v_mul_f32_e32 v102, v102, v102
	v_mul_f32_e32 v103, v103, v103
	v_mul_f32_e32 v104, v104, v104
	v_mul_f32_e32 v105, v105, v105
	v_mul_f32_e32 v97, v94, v94
	v_cvt_pk_bf16_f32 v94, v102, v103
	v_cvt_pk_bf16_f32 v95, v104, v105
	v_cvt_pk_bf16_f32 v96, v106, v107
	v_max_f32_e32 v90, 0, v90
	v_cvt_pk_bf16_f32 v97, v108, v97
	global_store_dwordx4 v[110:111], v[94:97], off offset:256
	v_max_f32_e32 v78, v78, v78
	v_max_f32_e32 v78, 0, v78
	v_max_f32_e32 v96, v98, v98
	v_max_f32_e32 v98, v100, v100
	v_mul_f32_e32 v100, v90, v90
	v_max_f32_e32 v90, v91, v91
	v_max_f32_e32 v90, 0, v90
	v_max_f32_e32 v97, v99, v99
	v_max_f32_e32 v99, v101, v101
	v_mul_f32_e32 v101, v90, v90
	v_max_f32_e32 v90, v92, v92
	v_or_b32_e32 v94, 32, v154
	v_max_f32_e32 v90, 0, v90
	v_ashrrev_i32_e32 v95, 31, v94
	v_mul_f32_e32 v102, v90, v90
	v_max_f32_e32 v90, v93, v93
	v_lshlrev_b64 v[94:95], 15, v[94:95]
	v_max_f32_e32 v96, 0, v96
	v_max_f32_e32 v97, 0, v97
	v_max_f32_e32 v90, 0, v90
	v_lshl_add_u64 v[94:95], v[156:157], 0, v[94:95]
	v_mul_f32_e32 v96, v96, v96
	v_mul_f32_e32 v97, v97, v97
	v_max_f32_e32 v98, 0, v98
	v_max_f32_e32 v99, 0, v99
	v_mul_f32_e32 v93, v90, v90
	v_cvt_pk_bf16_f32 v90, v96, v97
	v_mul_f32_e32 v98, v98, v98
	v_mul_f32_e32 v99, v99, v99
	v_cvt_pk_bf16_f32 v91, v98, v99
	v_cvt_pk_bf16_f32 v92, v100, v101
	v_cvt_pk_bf16_f32 v93, v102, v93
	global_store_dwordx4 v[94:95], v[90:93], off
	v_max_f32_e32 v86, v86, v86
	v_max_f32_e32 v87, v87, v87
	v_mul_f32_e32 v90, v78, v78
	v_max_f32_e32 v78, v79, v79
	v_max_f32_e32 v78, 0, v78
	v_mul_f32_e32 v91, v78, v78
	v_max_f32_e32 v78, v80, v80
	v_max_f32_e32 v78, 0, v78
	v_max_f32_e32 v88, v88, v88
	v_max_f32_e32 v89, v89, v89
	v_mul_f32_e32 v92, v78, v78
; __device__ __forceinline__ unsigned cvt_pk_bf16(float lo, float hi) { unsigned r; asm volatile("v_cvt_pk_bf16_f32 %0, %1, %2" : "=v"(r) : "v"(lo), "v"(hi)); return r; }
; template <int ACT> __device__ __forceinline__ f32x4 act4(f32x4 v, float sc) {
;     ...
;     { f32x4 o;
; #pragma unroll
;         for (int j = 0; j < 4; ++j) { const float t = v[j] > 0.f ? v[j] : 0.f; o[j] = t * t; }
;         return o; }
; }
; template <int ACT, int STAT> __device__ __forceinline__ void store_tile(const f32x4 (&acc)[2][2][4][2], bf16_t* base, int ldc, int row0, int col0, float sc, float* stat, int slot, int fq) {
; #pragma unroll
;     for (int ai = 0; ai < 2; ++ai)
; #pragma unroll
;         for (int m = 0; m < 4; ++m) { const int row = row0 + ai * HALF + m * 16; bf16_t* rowp = base + (size_t)row * ldc + col0; float s1 = 0.f, s2 = 0.f;
; #pragma unroll
;             for (int bj = 0; bj < 2; ++bj) { const f32x4 v0 = act4<ACT>(acc[ai][bj][m][0], sc), v1 = act4<ACT>(acc[ai][bj][m][1], sc);
;                 if (STAT) { s1 += (v0[0] + v0[1]) + (v0[2] + v0[3]) + (v1[0] + v1[1]) + (v1[2] + v1[3]);
;                             s2 += (v0[0] * v0[0] + v0[1] * v0[1]) + (v0[2] * v0[2] + v0[3] * v0[3]) + (v1[0] * v1[0] + v1[1] * v1[1]) + (v1[2] * v1[2] + v1[3] * v1[3]); }
;                 u32x4 w; w.x = cvt_pk_bf16(v0[0], v0[1]); w.y = cvt_pk_bf16(v0[2], v0[3]); w.z = cvt_pk_bf16(v1[0], v1[1]); w.w = cvt_pk_bf16(v1[2], v1[3]);
;                 *(u32x4*)(rowp + bj * HALF) = w; }
	v_max_f32_e32 v78, v81, v81
	v_max_f32_e32 v86, 0, v86
	v_max_f32_e32 v87, 0, v87
	v_max_f32_e32 v88, 0, v88
	v_max_f32_e32 v89, 0, v89
	v_max_f32_e32 v78, 0, v78
	v_max_f32_e32 v74, v74, v74
	v_mul_f32_e32 v86, v86, v86
	v_mul_f32_e32 v87, v87, v87
	v_mul_f32_e32 v88, v88, v88
	v_mul_f32_e32 v89, v89, v89
	v_mul_f32_e32 v81, v78, v78
	v_cvt_pk_bf16_f32 v78, v86, v87
	v_cvt_pk_bf16_f32 v79, v88, v89
	v_cvt_pk_bf16_f32 v80, v90, v91
	v_max_f32_e32 v74, 0, v74
	v_cvt_pk_bf16_f32 v81, v92, v81
	global_store_dwordx4 v[94:95], v[78:81], off offset:256
	v_max_f32_e32 v66, v66, v66
	v_max_f32_e32 v66, 0, v66
	v_max_f32_e32 v80, v82, v82
	v_max_f32_e32 v82, v84, v84
	v_mul_f32_e32 v84, v74, v74
	v_max_f32_e32 v74, v75, v75
	v_max_f32_e32 v74, 0, v74
	v_max_f32_e32 v81, v83, v83
	v_max_f32_e32 v83, v85, v85
	v_mul_f32_e32 v85, v74, v74
	v_max_f32_e32 v74, v76, v76
	v_or_b32_e32 v78, 48, v154
	v_max_f32_e32 v74, 0, v74
	v_ashrrev_i32_e32 v79, 31, v78
	v_mul_f32_e32 v86, v74, v74
	v_max_f32_e32 v74, v77, v77
	v_lshlrev_b64 v[78:79], 15, v[78:79]
	v_max_f32_e32 v80, 0, v80
	v_max_f32_e32 v81, 0, v81
	v_max_f32_e32 v74, 0, v74
	v_lshl_add_u64 v[78:79], v[156:157], 0, v[78:79]
	v_mul_f32_e32 v80, v80, v80
	v_mul_f32_e32 v81, v81, v81
	v_max_f32_e32 v82, 0, v82
	v_max_f32_e32 v83, 0, v83
	v_mul_f32_e32 v77, v74, v74
	v_cvt_pk_bf16_f32 v74, v80, v81
	v_mul_f32_e32 v82, v82, v82
	v_mul_f32_e32 v83, v83, v83
	v_cvt_pk_bf16_f32 v75, v82, v83
	v_cvt_pk_bf16_f32 v76, v84, v85
	v_cvt_pk_bf16_f32 v77, v86, v77
	global_store_dwordx4 v[78:79], v[74:77], off
	v_max_f32_e32 v70, v70, v70
	v_max_f32_e32 v71, v71, v71
	v_mul_f32_e32 v74, v66, v66
	v_max_f32_e32 v66, v67, v67
	v_max_f32_e32 v66, 0, v66
	v_mul_f32_e32 v75, v66, v66
	v_max_f32_e32 v66, v68, v68
	v_max_f32_e32 v66, 0, v66
	v_max_f32_e32 v72, v72, v72
	v_max_f32_e32 v73, v73, v73
	v_mul_f32_e32 v76, v66, v66
	v_max_f32_e32 v66, v69, v69
	v_max_f32_e32 v70, 0, v70
	v_max_f32_e32 v71, 0, v71
	v_max_f32_e32 v72, 0, v72
	v_max_f32_e32 v73, 0, v73
	v_max_f32_e32 v66, 0, v66
	v_max_f32_e32 v58, v58, v58
	v_mul_f32_e32 v70, v70, v70
	v_mul_f32_e32 v71, v71, v71
	v_mul_f32_e32 v72, v72, v72
	v_mul_f32_e32 v73, v73, v73
	v_mul_f32_e32 v69, v66, v66
	v_cvt_pk_bf16_f32 v66, v70, v71
	v_cvt_pk_bf16_f32 v67, v72, v73
	v_cvt_pk_bf16_f32 v68, v74, v75
	v_max_f32_e32 v58, 0, v58
	v_cvt_pk_bf16_f32 v69, v76, v69
	global_store_dwordx4 v[78:79], v[66:69], off offset:256
	v_max_f32_e32 v62, v62, v62
	v_max_f32_e32 v62, 0, v62
	v_mul_f32_e32 v68, v58, v58
	v_max_f32_e32 v58, v59, v59
	v_max_f32_e32 v58, 0, v58
	v_mul_f32_e32 v69, v58, v58
	v_max_f32_e32 v58, v60, v60
	v_max_f32_e32 v58, 0, v58
	v_max_f32_e32 v63, v63, v63
	v_mul_f32_e32 v70, v58, v58
	v_max_f32_e32 v58, v61, v61
	v_mul_f32_e32 v62, v62, v62
	v_max_f32_e32 v63, 0, v63
	v_max_f32_e32 v58, 0, v58
	v_mul_f32_e32 v63, v63, v63
	v_max_f32_e32 v64, v64, v64
	v_max_f32_e32 v65, v65, v65
	v_mul_f32_e32 v61, v58, v58
	v_cvt_pk_bf16_f32 v58, v62, v63
	v_add_co_u32_e32 v62, vcc, s54, v146
	v_max_f32_e32 v46, v46, v46
	v_max_f32_e32 v64, 0, v64
	v_max_f32_e32 v65, 0, v65
	v_addc_co_u32_e32 v63, vcc, 0, v147, vcc
	v_max_f32_e32 v46, 0, v46
	v_mul_f32_e32 v64, v64, v64
	v_mul_f32_e32 v65, v65, v65
	v_cvt_pk_bf16_f32 v59, v64, v65
	v_cvt_pk_bf16_f32 v60, v68, v69
	v_cvt_pk_bf16_f32 v61, v70, v61
	global_store_dwordx4 v[62:63], v[58:61], off
	v_max_f32_e32 v54, v54, v54
	v_max_f32_e32 v55, v55, v55
	v_mul_f32_e32 v58, v46, v46
	v_max_f32_e32 v46, v47, v47
	v_max_f32_e32 v46, 0, v46
	v_mul_f32_e32 v59, v46, v46
	v_max_f32_e32 v46, v48, v48
	v_max_f32_e32 v46, 0, v46
	v_max_f32_e32 v56, v56, v56
	v_max_f32_e32 v57, v57, v57
	v_mul_f32_e32 v60, v46, v46
	v_max_f32_e32 v46, v49, v49
	v_max_f32_e32 v54, 0, v54
	v_max_f32_e32 v55, 0, v55
	v_max_f32_e32 v56, 0, v56
	v_max_f32_e32 v57, 0, v57
	v_max_f32_e32 v46, 0, v46
	v_max_f32_e32 v42, v42, v42
	v_lshl_add_u64 v[66:67], v[146:147], 0, s[20:21]
	v_mul_f32_e32 v54, v54, v54
	v_mul_f32_e32 v55, v55, v55
	v_mul_f32_e32 v56, v56, v56
	v_mul_f32_e32 v57, v57, v57
	v_mul_f32_e32 v49, v46, v46
	v_cvt_pk_bf16_f32 v46, v54, v55
	v_cvt_pk_bf16_f32 v47, v56, v57
	v_cvt_pk_bf16_f32 v48, v58, v59
	v_max_f32_e32 v42, 0, v42
	v_cvt_pk_bf16_f32 v49, v60, v49
	global_store_dwordx4 v[66:67], v[46:49], off offset:256
	v_max_f32_e32 v30, v30, v30
	v_max_f32_e32 v30, 0, v30
	v_max_f32_e32 v48, v50, v50
	v_max_f32_e32 v50, v52, v52
	v_mul_f32_e32 v52, v42, v42
	v_max_f32_e32 v42, v43, v43
	v_max_f32_e32 v42, 0, v42
	v_max_f32_e32 v49, v51, v51
	v_max_f32_e32 v51, v53, v53
	v_mul_f32_e32 v53, v42, v42
	v_max_f32_e32 v42, v44, v44
	v_max_f32_e32 v42, 0, v42
	v_max_f32_e32 v48, 0, v48
	v_mul_f32_e32 v54, v42, v42
	v_max_f32_e32 v42, v45, v45
	v_mul_f32_e32 v48, v48, v48
	v_max_f32_e32 v49, 0, v49
	v_max_f32_e32 v42, 0, v42
	v_mul_f32_e32 v49, v49, v49
	v_mul_f32_e32 v45, v42, v42
	v_cvt_pk_bf16_f32 v42, v48, v49
	v_add_co_u32_e32 v48, vcc, s55, v146
	v_max_f32_e32 v50, 0, v50
; __device__ __forceinline__ unsigned cvt_pk_bf16(float lo, float hi) { unsigned r; asm volatile("v_cvt_pk_bf16_f32 %0, %1, %2" : "=v"(r) : "v"(lo), "v"(hi)); return r; }
; #define PG8_BAR __builtin_amdgcn_s_barrier()
; template <int ACT> __device__ __forceinline__ f32x4 act4(f32x4 v, float sc) {
;     ...
;     { f32x4 o;
; #pragma unroll
;         for (int j = 0; j < 4; ++j) { const float t = v[j] > 0.f ? v[j] : 0.f; o[j] = t * t; }
;         return o; }
; }
; template <int ACT, int STAT> __device__ __forceinline__ void store_tile(const f32x4 (&acc)[2][2][4][2], bf16_t* base, int ldc, int row0, int col0, float sc, float* stat, int slot, int fq) {
; #pragma unroll
;     for (int ai = 0; ai < 2; ++ai)
; #pragma unroll
;         for (int m = 0; m < 4; ++m) { const int row = row0 + ai * HALF + m * 16; bf16_t* rowp = base + (size_t)row * ldc + col0; float s1 = 0.f, s2 = 0.f;
; #pragma unroll
;             for (int bj = 0; bj < 2; ++bj) { const f32x4 v0 = act4<ACT>(acc[ai][bj][m][0], sc), v1 = act4<ACT>(acc[ai][bj][m][1], sc);
;                 if (STAT) { s1 += (v0[0] + v0[1]) + (v0[2] + v0[3]) + (v1[0] + v1[1]) + (v1[2] + v1[3]);
;                             s2 += (v0[0] * v0[0] + v0[1] * v0[1]) + (v0[2] * v0[2] + v0[3] * v0[3]) + (v1[0] * v1[0] + v1[1] * v1[1]) + (v1[2] * v1[2] + v1[3] * v1[3]); }
;                 u32x4 w; w.x = cvt_pk_bf16(v0[0], v0[1]); w.y = cvt_pk_bf16(v0[2], v0[3]); w.z = cvt_pk_bf16(v1[0], v1[1]); w.w = cvt_pk_bf16(v1[2], v1[3]);
;                 *(u32x4*)(rowp + bj * HALF) = w; }
; template <class Epi, class Sched, bool ALIGN_EPI = false, bool SP2 = false>
; __device__ __forceinline__ void gemm_phase(PG8_LAS unsigned char* lds, const Gemm g, const Sched& S, const Epi& E) {
;     ...
;         if (!has_next) break;
; #pragma unroll
;         for (int a = 0; a < 2; ++a)
; #pragma unroll
;             for (int b = 0; b < 2; ++b)
; #pragma unroll
;                 for (int m = 0; m < 4; ++m)
; #pragma unroll
;                     for (int n = 0; n < 2; ++n) acc[a][b][m][n] = (f32x4){0.f, 0.f, 0.f, 0.f};
;         cur = nxt; cA = nA; cB = nB; ++ui;
;         if constexpr (ALIGN_EPI) { if (wr == 1) PG8_BAR; }
	v_max_f32_e32 v51, 0, v51
	v_addc_co_u32_e32 v49, vcc, 0, v147, vcc
	v_mul_f32_e32 v50, v50, v50
	v_mul_f32_e32 v51, v51, v51
	v_cvt_pk_bf16_f32 v43, v50, v51
	v_cvt_pk_bf16_f32 v44, v52, v53
	v_cvt_pk_bf16_f32 v45, v54, v45
	global_store_dwordx4 v[48:49], v[42:45], off
	v_max_f32_e32 v38, v38, v38
	v_max_f32_e32 v39, v39, v39
	v_mul_f32_e32 v42, v30, v30
	v_max_f32_e32 v30, v31, v31
	v_max_f32_e32 v30, 0, v30
	v_mul_f32_e32 v43, v30, v30
	v_max_f32_e32 v30, v32, v32
	v_max_f32_e32 v30, 0, v30
	v_max_f32_e32 v40, v40, v40
	v_max_f32_e32 v41, v41, v41
	v_mul_f32_e32 v44, v30, v30
	v_max_f32_e32 v30, v33, v33
	v_max_f32_e32 v38, 0, v38
	v_max_f32_e32 v39, 0, v39
	v_max_f32_e32 v40, 0, v40
	v_max_f32_e32 v41, 0, v41
	v_max_f32_e32 v30, 0, v30
	v_max_f32_e32 v26, v26, v26
	v_lshl_add_u64 v[46:47], v[146:147], 0, s[22:23]
	v_mul_f32_e32 v38, v38, v38
	v_mul_f32_e32 v39, v39, v39
	v_mul_f32_e32 v40, v40, v40
	v_mul_f32_e32 v41, v41, v41
	v_mul_f32_e32 v33, v30, v30
	v_cvt_pk_bf16_f32 v30, v38, v39
	v_cvt_pk_bf16_f32 v31, v40, v41
	v_cvt_pk_bf16_f32 v32, v42, v43
	v_max_f32_e32 v26, 0, v26
	v_cvt_pk_bf16_f32 v33, v44, v33
	global_store_dwordx4 v[46:47], v[30:33], off offset:256
	v_max_f32_e32 v14, v14, v14
	v_max_f32_e32 v14, 0, v14
	v_max_f32_e32 v32, v34, v34
	v_max_f32_e32 v34, v36, v36
	v_mul_f32_e32 v36, v26, v26
	v_max_f32_e32 v26, v27, v27
	v_max_f32_e32 v26, 0, v26
	v_max_f32_e32 v33, v35, v35
	v_max_f32_e32 v35, v37, v37
	v_mul_f32_e32 v37, v26, v26
	v_max_f32_e32 v26, v28, v28
	v_max_f32_e32 v26, 0, v26
	v_max_f32_e32 v32, 0, v32
	v_mul_f32_e32 v38, v26, v26
	v_max_f32_e32 v26, v29, v29
	v_mul_f32_e32 v32, v32, v32
	v_max_f32_e32 v33, 0, v33
	v_max_f32_e32 v26, 0, v26
	v_mul_f32_e32 v33, v33, v33
	v_mul_f32_e32 v29, v26, v26
	v_cvt_pk_bf16_f32 v26, v32, v33
	v_add_co_u32_e32 v32, vcc, s56, v146
	v_max_f32_e32 v34, 0, v34
	v_max_f32_e32 v35, 0, v35
	v_addc_co_u32_e32 v33, vcc, 0, v147, vcc
	v_mul_f32_e32 v34, v34, v34
	v_mul_f32_e32 v35, v35, v35
	v_cvt_pk_bf16_f32 v27, v34, v35
	v_cvt_pk_bf16_f32 v28, v36, v37
	v_cvt_pk_bf16_f32 v29, v38, v29
	global_store_dwordx4 v[32:33], v[26:29], off
	v_max_f32_e32 v22, v22, v22
	v_max_f32_e32 v23, v23, v23
	v_mul_f32_e32 v26, v14, v14
	v_max_f32_e32 v14, v15, v15
	v_max_f32_e32 v14, 0, v14
	v_mul_f32_e32 v27, v14, v14
	v_max_f32_e32 v14, v16, v16
	v_max_f32_e32 v14, 0, v14
	v_max_f32_e32 v24, v24, v24
	v_max_f32_e32 v25, v25, v25
	v_mul_f32_e32 v28, v14, v14
	v_max_f32_e32 v14, v17, v17
	v_max_f32_e32 v22, 0, v22
	v_max_f32_e32 v23, 0, v23
	v_max_f32_e32 v24, 0, v24
	v_max_f32_e32 v25, 0, v25
	v_max_f32_e32 v14, 0, v14
	v_max_f32_e32 v10, v10, v10
	v_lshl_add_u64 v[30:31], v[146:147], 0, s[24:25]
	v_mul_f32_e32 v22, v22, v22
	v_mul_f32_e32 v23, v23, v23
	v_mul_f32_e32 v24, v24, v24
	v_mul_f32_e32 v25, v25, v25
	v_mul_f32_e32 v17, v14, v14
	v_cvt_pk_bf16_f32 v14, v22, v23
	v_cvt_pk_bf16_f32 v15, v24, v25
	v_cvt_pk_bf16_f32 v16, v26, v27
	v_max_f32_e32 v10, 0, v10
	v_cvt_pk_bf16_f32 v17, v28, v17
	global_store_dwordx4 v[30:31], v[14:17], off offset:256
	v_max_f32_e32 v2, v2, v2
	v_max_f32_e32 v2, 0, v2
	v_max_f32_e32 v16, v18, v18
	v_max_f32_e32 v18, v20, v20
	v_mul_f32_e32 v20, v10, v10
	v_max_f32_e32 v10, v11, v11
	v_max_f32_e32 v10, 0, v10
	v_max_f32_e32 v17, v19, v19
	v_max_f32_e32 v19, v21, v21
	v_mul_f32_e32 v21, v10, v10
	v_max_f32_e32 v10, v12, v12
	v_max_f32_e32 v10, 0, v10
	v_max_f32_e32 v16, 0, v16
	v_mul_f32_e32 v22, v10, v10
	v_max_f32_e32 v10, v13, v13
	v_mul_f32_e32 v16, v16, v16
	v_max_f32_e32 v17, 0, v17
	v_max_f32_e32 v10, 0, v10
	v_mul_f32_e32 v17, v17, v17
	v_mul_f32_e32 v13, v10, v10
	v_cvt_pk_bf16_f32 v10, v16, v17
	v_add_co_u32_e32 v16, vcc, s57, v146
	v_max_f32_e32 v18, 0, v18
	v_max_f32_e32 v19, 0, v19
	v_addc_co_u32_e32 v17, vcc, 0, v147, vcc
	v_mul_f32_e32 v18, v18, v18
	v_mul_f32_e32 v19, v19, v19
	v_cvt_pk_bf16_f32 v11, v18, v19
	v_cvt_pk_bf16_f32 v12, v20, v21
	v_cvt_pk_bf16_f32 v13, v22, v13
	global_store_dwordx4 v[16:17], v[10:13], off
	v_max_f32_e32 v6, v6, v6
	v_max_f32_e32 v7, v7, v7
	v_mul_f32_e32 v10, v2, v2
	v_max_f32_e32 v2, v3, v3
	v_max_f32_e32 v2, 0, v2
	v_mul_f32_e32 v11, v2, v2
	v_max_f32_e32 v2, v4, v4
	v_max_f32_e32 v2, 0, v2
	v_mul_f32_e32 v12, v2, v2
	v_max_f32_e32 v2, v5, v5
	v_max_f32_e32 v8, v8, v8
	v_max_f32_e32 v9, v9, v9
	v_max_f32_e32 v2, 0, v2
	v_lshl_add_u64 v[14:15], v[146:147], 0, s[26:27]
	v_max_f32_e32 v6, 0, v6
	v_max_f32_e32 v7, 0, v7
	v_max_f32_e32 v8, 0, v8
	v_max_f32_e32 v9, 0, v9
	v_mul_f32_e32 v5, v2, v2
	s_andn2_b64 vcc, exec, s[0:1]
	s_mov_b64 s[0:1], -1
	v_mul_f32_e32 v6, v6, v6
	v_mul_f32_e32 v7, v7, v7
	v_mul_f32_e32 v8, v8, v8
	v_mul_f32_e32 v9, v9, v9
	v_cvt_pk_bf16_f32 v2, v6, v7
	v_cvt_pk_bf16_f32 v3, v8, v9
	v_cvt_pk_bf16_f32 v4, v10, v11
	v_cvt_pk_bf16_f32 v5, v12, v5
	global_store_dwordx4 v[14:15], v[2:5], off offset:256
	s_cbranch_vccnz .LBB0_984
	s_andn2_b64 vcc, exec, s[6:7]
	s_cbranch_vccnz .LBB0_983
	s_branch .LBB0_983
